# P5/P8 GEMM epilogues: row sum-of-squares lane reduction via v_permlane16/32_swap + add instead of ds_bpermute + LDS wait (same pairs added)
# baseline (speedup 1.0000x reference)
; #define PG8_STAGE(bufoff, gbase, voff) do { _Pragma("unroll") for (int _i = 0; _i < 2; ++_i) \
;         __builtin_amdgcn_global_load_lds((const unsigned*)((const char*)(gbase) + (voff)[_i]), (LAS unsigned*)(lds + (bufoff) + ldsw + _i * 8192), 16, 0, 0); } while (0)
; #define PG8_LDA(dst, b, h) do { _Pragma("unroll") for (int m = 0; m < 4; ++m) _Pragma("unroll") for (int k = 0; k < 2; ++k) dst[m][k] = *(const LAS bf16x8*)(lds + PG8_SA(b, h) + aoff + m * 2048 + k * 1024); } while (0)
; #define PG8_LDB(dst, b, h) do { _Pragma("unroll") for (int n = 0; n < 2; ++n) _Pragma("unroll") for (int k = 0; k < 2; ++k) dst[n][k] = *(const LAS bf16x8*)(lds + PG8_SB(b, h) + boff + n * 2048 + k * 1024); } while (0)
; #define PG8_MMA(ai, bj, At, Bt) do { __builtin_amdgcn_s_setprio(1); _Pragma("unroll") for (int m = 0; m < 4; ++m) _Pragma("unroll") for (int n = 0; n < 2; ++n) _Pragma("unroll") for (int k = 0; k < 2; ++k) \
;         acc[ai][bj][m][n] = __builtin_amdgcn_mfma_f32_16x16x32_bf16(Bt[n][k], At[m][k], acc[ai][bj][m][n], 0, 0, 0); __builtin_amdgcn_s_setprio(0); } while (0)
; #define PG8_WAIT_L(n) asm volatile("s_waitcnt lgkmcnt(" #n ")" ::: "memory")
; #define PG8_BAR __builtin_amdgcn_s_barrier()
; #define PG8_SCHED __builtin_amdgcn_sched_barrier(0)
; template <class Epi>
; __device__ __forceinline__ void gemm_phase(LAS unsigned char* lds, const Gemm g, const StaticOrder& S, const Epi& E) {
;     ...
;             PG8_LDB(B0, 0, 0); PG8_SCHED; PG8_LDA(At, 0, 0); PG8_STAGE(PG8_SA(1, 1), a1 + hstepA, voffA);
;             PG8_WAIT_L(8); PG8_BAR; PG8_WAIT_L(0); PG8_MMA(0, 0, At, B0); PG8_BAR; PG8_SCHED;
;             PG8_LDB(B1, 0, 1); PG8_STAGE(PG8_SB(0, 0), b2, voffB);
;             PG8_BAR; PG8_WAIT_L(0); PG8_MMA(0, 1, At, B1); PG8_BAR;
;             PG8_LDA(At, 0, 1); PG8_STAGE(PG8_SA(0, 0), a2, voffA);
;             PG8_BAR; PG8_WAIT_L(0); PG8_MMA(1, 0, At, B0); PG8_BAR; PG8_SCHED;
.LBB0_967:
	ds_read_b128 v[144:147], v154
	ds_read_b128 v[158:161], v154 offset:1024
	ds_read_b128 v[162:165], v154 offset:2048
	ds_read_b128 v[166:169], v154 offset:3072
	s_add_u32 s36, s34, 0xfffc0080
	s_addc_u32 s37, s35, -1
	s_cmp_eq_u32 s52, 12
	s_cselect_b32 s39, s15, s37
	s_cselect_b32 s38, s25, s36
	s_cselect_b32 s37, s13, s51
	s_cselect_b32 s36, s49, s50
	v_lshl_add_u64 v[174:175], s[34:35], 0, v[136:137]
	s_add_i32 m0, s29, 0xc000
	ds_read_b128 v[170:173], v155
	ds_read_b128 v[178:181], v155 offset:1024
	ds_read_b128 v[182:185], v155 offset:2048
	ds_read_b128 v[186:189], v155 offset:3072
	ds_read_b128 v[190:193], v155 offset:4096
	ds_read_b128 v[194:197], v155 offset:5120
	ds_read_b128 v[198:201], v155 offset:6144
	ds_read_b128 v[202:205], v155 offset:7168
	global_load_lds_dwordx4 v[174:175], off
	v_lshl_add_u64 v[174:175], s[34:35], 0, v[138:139]
	s_add_i32 m0, s29, 0xe000
	s_nop 0
	global_load_lds_dwordx4 v[174:175], off
	s_waitcnt lgkmcnt(8)
	s_barrier
	s_waitcnt lgkmcnt(0)
	s_setprio 1
	s_waitcnt lgkmcnt(0)
	v_mfma_f32_16x16x32_bf16 v[124:127], v[144:147], v[170:173], v[124:127]
	v_mfma_f32_16x16x32_bf16 v[120:123], v[162:165], v[170:173], v[120:123]
	v_mfma_f32_16x16x32_bf16 v[108:111], v[144:147], v[182:185], v[108:111]
	v_mfma_f32_16x16x32_bf16 v[104:107], v[162:165], v[182:185], v[104:107]
	v_mfma_f32_16x16x32_bf16 v[92:95], v[144:147], v[190:193], v[92:95]
	v_mfma_f32_16x16x32_bf16 v[88:91], v[162:165], v[190:193], v[88:91]
	v_mfma_f32_16x16x32_bf16 v[76:79], v[144:147], v[198:201], v[76:79]
	v_mfma_f32_16x16x32_bf16 v[72:75], v[162:165], v[198:201], v[72:75]
	v_mfma_f32_16x16x32_bf16 v[124:127], v[158:161], v[178:181], v[124:127]
	v_mfma_f32_16x16x32_bf16 v[120:123], v[166:169], v[178:181], v[120:123]
	v_mfma_f32_16x16x32_bf16 v[108:111], v[158:161], v[186:189], v[108:111]
	v_mfma_f32_16x16x32_bf16 v[104:107], v[166:169], v[186:189], v[104:107]
	v_mfma_f32_16x16x32_bf16 v[92:95], v[158:161], v[194:197], v[92:95]
	v_mfma_f32_16x16x32_bf16 v[88:91], v[166:169], v[194:197], v[88:91]
	v_mfma_f32_16x16x32_bf16 v[76:79], v[158:161], v[202:205], v[76:79]
	v_mfma_f32_16x16x32_bf16 v[72:75], v[166:169], v[202:205], v[72:75]
	s_setprio 0
	s_barrier
	s_add_i32 s53, s47, s28
	v_lshl_add_u64 v[174:175], s[36:37], 0, v[130:131]
	s_mov_b32 m0, s53
	ds_read_b128 v[206:209], v156
	ds_read_b128 v[210:213], v156 offset:1024
	ds_read_b128 v[214:217], v156 offset:2048
	ds_read_b128 v[218:221], v156 offset:3072
	global_load_lds_dwordx4 v[174:175], off
	v_lshl_add_u64 v[222:223], s[36:37], 0, v[134:135]
	s_add_i32 m0, s53, 0x2000
	s_nop 0
	global_load_lds_dwordx4 v[222:223], off
	s_barrier
	s_waitcnt lgkmcnt(0)
	s_setprio 1
	s_waitcnt lgkmcnt(0)
	v_mfma_f32_16x16x32_bf16 v[116:119], v[206:209], v[170:173], v[116:119]
	v_mfma_f32_16x16x32_bf16 v[112:115], v[214:217], v[170:173], v[112:115]
	v_mfma_f32_16x16x32_bf16 v[100:103], v[206:209], v[182:185], v[100:103]
	v_mfma_f32_16x16x32_bf16 v[96:99], v[214:217], v[182:185], v[96:99]
	v_mfma_f32_16x16x32_bf16 v[84:87], v[206:209], v[190:193], v[84:87]
	v_mfma_f32_16x16x32_bf16 v[80:83], v[214:217], v[190:193], v[80:83]
	v_mfma_f32_16x16x32_bf16 v[68:71], v[206:209], v[198:201], v[68:71]
	v_mfma_f32_16x16x32_bf16 v[64:67], v[214:217], v[198:201], v[64:67]
	v_mfma_f32_16x16x32_bf16 v[116:119], v[210:213], v[178:181], v[116:119]
	v_mfma_f32_16x16x32_bf16 v[112:115], v[218:221], v[178:181], v[112:115]
	v_mfma_f32_16x16x32_bf16 v[100:103], v[210:213], v[186:189], v[100:103]
	v_mfma_f32_16x16x32_bf16 v[96:99], v[218:221], v[186:189], v[96:99]
	v_mfma_f32_16x16x32_bf16 v[84:87], v[210:213], v[194:197], v[84:87]
	v_mfma_f32_16x16x32_bf16 v[80:83], v[218:221], v[194:197], v[80:83]
	v_mfma_f32_16x16x32_bf16 v[68:71], v[210:213], v[202:205], v[68:71]
	v_mfma_f32_16x16x32_bf16 v[64:67], v[218:221], v[202:205], v[64:67]
	s_setprio 0
	s_mov_b32 m0, s29
	v_lshl_add_u64 v[224:225], s[38:39], 0, v[128:129]
	s_barrier
	ds_read_b128 v[170:173], v155 offset:16384
	ds_read_b128 v[178:181], v155 offset:17408
	ds_read_b128 v[182:185], v155 offset:18432
	ds_read_b128 v[186:189], v155 offset:19456
	ds_read_b128 v[190:193], v155 offset:20480
	ds_read_b128 v[194:197], v155 offset:21504
	ds_read_b128 v[198:201], v155 offset:22528
	ds_read_b128 v[202:205], v155 offset:23552
	global_load_lds_dwordx4 v[224:225], off
	v_lshl_add_u64 v[226:227], s[38:39], 0, v[132:133]
	s_mov_b32 m0, s31
	s_nop 0
	global_load_lds_dwordx4 v[226:227], off
	s_barrier
	s_waitcnt lgkmcnt(0)
	s_setprio 1
	s_waitcnt lgkmcnt(0)
	v_mfma_f32_16x16x32_bf16 v[60:63], v[144:147], v[170:173], v[60:63]
	v_mfma_f32_16x16x32_bf16 v[56:59], v[162:165], v[170:173], v[56:59]
	v_mfma_f32_16x16x32_bf16 v[44:47], v[144:147], v[182:185], v[44:47]
	v_mfma_f32_16x16x32_bf16 v[40:43], v[162:165], v[182:185], v[40:43]
	v_mfma_f32_16x16x32_bf16 v[28:31], v[144:147], v[190:193], v[28:31]
	v_mfma_f32_16x16x32_bf16 v[24:27], v[162:165], v[190:193], v[24:27]
	v_mfma_f32_16x16x32_bf16 v[12:15], v[144:147], v[198:201], v[12:15]
	v_mfma_f32_16x16x32_bf16 v[8:11], v[162:165], v[198:201], v[8:11]
	v_mfma_f32_16x16x32_bf16 v[60:63], v[158:161], v[178:181], v[60:63]
	v_mfma_f32_16x16x32_bf16 v[56:59], v[166:169], v[178:181], v[56:59]
	v_mfma_f32_16x16x32_bf16 v[44:47], v[158:161], v[186:189], v[44:47]
	v_mfma_f32_16x16x32_bf16 v[40:43], v[166:169], v[186:189], v[40:43]
	v_mfma_f32_16x16x32_bf16 v[28:31], v[158:161], v[194:197], v[28:31]
	v_mfma_f32_16x16x32_bf16 v[24:27], v[166:169], v[194:197], v[24:27]
	v_mfma_f32_16x16x32_bf16 v[12:15], v[158:161], v[202:205], v[12:15]
	v_mfma_f32_16x16x32_bf16 v[8:11], v[166:169], v[202:205], v[8:11]
	s_setprio 0
	s_barrier
; #define PG8_STAGE(bufoff, gbase, voff) do { _Pragma("unroll") for (int _i = 0; _i < 2; ++_i) \
;         __builtin_amdgcn_global_load_lds((const unsigned*)((const char*)(gbase) + (voff)[_i]), (LAS unsigned*)(lds + (bufoff) + ldsw + _i * 8192), 16, 0, 0); } while (0)
; #define PG8_LDA(dst, b, h) do { _Pragma("unroll") for (int m = 0; m < 4; ++m) _Pragma("unroll") for (int k = 0; k < 2; ++k) dst[m][k] = *(const LAS bf16x8*)(lds + PG8_SA(b, h) + aoff + m * 2048 + k * 1024); } while (0)
; #define PG8_LDB(dst, b, h) do { _Pragma("unroll") for (int n = 0; n < 2; ++n) _Pragma("unroll") for (int k = 0; k < 2; ++k) dst[n][k] = *(const LAS bf16x8*)(lds + PG8_SB(b, h) + boff + n * 2048 + k * 1024); } while (0)
; #define PG8_MMA(ai, bj, At, Bt) do { __builtin_amdgcn_s_setprio(1); _Pragma("unroll") for (int m = 0; m < 4; ++m) _Pragma("unroll") for (int n = 0; n < 2; ++n) _Pragma("unroll") for (int k = 0; k < 2; ++k) \
;         acc[ai][bj][m][n] = __builtin_amdgcn_mfma_f32_16x16x32_bf16(Bt[n][k], At[m][k], acc[ai][bj][m][n], 0, 0, 0); __builtin_amdgcn_s_setprio(0); } while (0)
; #define PG8_WAIT_V(n) asm volatile("s_waitcnt vmcnt(" #n ")" ::: "memory")
; #define PG8_WAIT_L(n) asm volatile("s_waitcnt lgkmcnt(" #n ")" ::: "memory")
; #define PG8_BAR __builtin_amdgcn_s_barrier()
; #define PG8_SCHED __builtin_amdgcn_sched_barrier(0)
; template <class Epi>
; __device__ __forceinline__ void gemm_phase(LAS unsigned char* lds, const Gemm g, const StaticOrder& S, const Epi& E) {
;     ...
;             PG8_STAGE(PG8_SB(0, 1), b2 + hstepB, voffB);
;             PG8_WAIT_V(6); PG8_BAR; PG8_MMA(1, 1, At, B1); PG8_BAR;
;             PG8_LDB(B0, 1, 0); PG8_SCHED; PG8_LDA(At, 1, 0); PG8_STAGE(PG8_SA(0, 1), a2 + hstepA, voffA);
;             PG8_WAIT_L(8); PG8_BAR; PG8_WAIT_L(0); PG8_MMA(0, 0, At, B0); PG8_BAR; PG8_SCHED;
;             PG8_LDB(B1, 1, 1); PG8_STAGE(PG8_SB(1, 0), b3, voffB);
;             PG8_BAR; PG8_WAIT_L(0); PG8_MMA(0, 1, At, B1); PG8_BAR;
;             PG8_LDA(At, 1, 1); PG8_STAGE(PG8_SA(1, 0), a3, voffA);
	s_add_u32 s54, s36, 0x40000
	s_addc_u32 s55, s37, 0
	s_add_i32 s53, s48, s28
	v_lshl_add_u64 v[144:145], s[54:55], 0, v[130:131]
	s_mov_b32 m0, s53
	s_nop 0
	global_load_lds_dwordx4 v[144:145], off
	v_lshl_add_u64 v[144:145], s[54:55], 0, v[134:135]
	s_add_i32 m0, s53, 0x2000
	s_nop 0
	global_load_lds_dwordx4 v[144:145], off
	s_waitcnt vmcnt(6)
	s_barrier
	s_setprio 1
	v_mfma_f32_16x16x32_bf16 v[52:55], v[206:209], v[170:173], v[52:55]
	v_mfma_f32_16x16x32_bf16 v[48:51], v[214:217], v[170:173], v[48:51]
	v_mfma_f32_16x16x32_bf16 v[36:39], v[206:209], v[182:185], v[36:39]
	v_mfma_f32_16x16x32_bf16 v[32:35], v[214:217], v[182:185], v[32:35]
	v_mfma_f32_16x16x32_bf16 v[20:23], v[206:209], v[190:193], v[20:23]
	v_mfma_f32_16x16x32_bf16 v[16:19], v[214:217], v[190:193], v[16:19]
	v_mfma_f32_16x16x32_bf16 v[4:7], v[206:209], v[198:201], v[4:7]
	v_mfma_f32_16x16x32_bf16 v[0:3], v[214:217], v[198:201], v[0:3]
	v_mfma_f32_16x16x32_bf16 v[52:55], v[210:213], v[178:181], v[52:55]
	v_mfma_f32_16x16x32_bf16 v[48:51], v[218:221], v[178:181], v[48:51]
	v_mfma_f32_16x16x32_bf16 v[36:39], v[210:213], v[186:189], v[36:39]
	v_mfma_f32_16x16x32_bf16 v[32:35], v[218:221], v[186:189], v[32:35]
	v_mfma_f32_16x16x32_bf16 v[20:23], v[210:213], v[194:197], v[20:23]
	v_mfma_f32_16x16x32_bf16 v[16:19], v[218:221], v[194:197], v[16:19]
	v_mfma_f32_16x16x32_bf16 v[4:7], v[210:213], v[202:205], v[4:7]
	v_mfma_f32_16x16x32_bf16 v[0:3], v[218:221], v[202:205], v[0:3]
	s_setprio 0
	s_add_i32 s53, 0, 0x18000
	v_add_u32_e32 v166, s53, v152
	s_barrier
	ds_read_b128 v[144:147], v166
	ds_read_b128 v[158:161], v166 offset:1024
	ds_read_b128 v[162:165], v166 offset:2048
	ds_read_b128 v[166:169], v166 offset:3072
	s_add_u32 s38, s38, 0x40000
	s_addc_u32 s39, s39, 0
	s_mov_b32 m0, s33
	v_lshl_add_u64 v[206:207], s[38:39], 0, v[128:129]
	ds_read_b128 v[170:173], v155 offset:32768
	ds_read_b128 v[178:181], v155 offset:33792
	ds_read_b128 v[182:185], v155 offset:34816
	ds_read_b128 v[186:189], v155 offset:35840
	ds_read_b128 v[190:193], v155 offset:36864
	ds_read_b128 v[194:197], v155 offset:37888
	ds_read_b128 v[198:201], v155 offset:38912
	ds_read_b128 v[202:205], v155 offset:39936
	global_load_lds_dwordx4 v[206:207], off
	v_lshl_add_u64 v[206:207], s[38:39], 0, v[132:133]
	s_mov_b32 m0, s40
	s_nop 0
	global_load_lds_dwordx4 v[206:207], off
	s_waitcnt lgkmcnt(8)
	s_barrier
	s_waitcnt lgkmcnt(0)
	s_setprio 1
	s_waitcnt lgkmcnt(0)
	v_mfma_f32_16x16x32_bf16 v[124:127], v[144:147], v[170:173], v[124:127]
	v_mfma_f32_16x16x32_bf16 v[120:123], v[162:165], v[170:173], v[120:123]
	v_mfma_f32_16x16x32_bf16 v[108:111], v[144:147], v[182:185], v[108:111]
	v_mfma_f32_16x16x32_bf16 v[104:107], v[162:165], v[182:185], v[104:107]
	v_mfma_f32_16x16x32_bf16 v[92:95], v[144:147], v[190:193], v[92:95]
	v_mfma_f32_16x16x32_bf16 v[88:91], v[162:165], v[190:193], v[88:91]
	v_mfma_f32_16x16x32_bf16 v[76:79], v[144:147], v[198:201], v[76:79]
	v_mfma_f32_16x16x32_bf16 v[72:75], v[162:165], v[198:201], v[72:75]
	v_mfma_f32_16x16x32_bf16 v[124:127], v[158:161], v[178:181], v[124:127]
	v_mfma_f32_16x16x32_bf16 v[120:123], v[166:169], v[178:181], v[120:123]
	v_mfma_f32_16x16x32_bf16 v[108:111], v[158:161], v[186:189], v[108:111]
	v_mfma_f32_16x16x32_bf16 v[104:107], v[166:169], v[186:189], v[104:107]
	v_mfma_f32_16x16x32_bf16 v[92:95], v[158:161], v[194:197], v[92:95]
	v_mfma_f32_16x16x32_bf16 v[88:91], v[166:169], v[194:197], v[88:91]
	v_mfma_f32_16x16x32_bf16 v[76:79], v[158:161], v[202:205], v[76:79]
	v_mfma_f32_16x16x32_bf16 v[72:75], v[166:169], v[202:205], v[72:75]
	s_setprio 0
	s_barrier
	s_add_i32 s38, 0, 0x1c000
	s_add_i32 s39, s53, s28
	v_add_u32_e32 v218, s38, v152
	v_lshl_add_u64 v[174:175], v[174:175], 0, s[10:11]
	s_mov_b32 m0, s39
	ds_read_b128 v[206:209], v218
	ds_read_b128 v[210:213], v218 offset:1024
	ds_read_b128 v[214:217], v218 offset:2048
	ds_read_b128 v[218:221], v218 offset:3072
	global_load_lds_dwordx4 v[174:175], off
	v_lshl_add_u64 v[174:175], v[222:223], 0, s[10:11]
	s_add_i32 m0, s39, 0x2000
	s_nop 0
	global_load_lds_dwordx4 v[174:175], off
	s_barrier
	s_waitcnt lgkmcnt(0)
	s_setprio 1
	s_waitcnt lgkmcnt(0)
	v_mfma_f32_16x16x32_bf16 v[116:119], v[206:209], v[170:173], v[116:119]
	v_mfma_f32_16x16x32_bf16 v[112:115], v[214:217], v[170:173], v[112:115]
	v_mfma_f32_16x16x32_bf16 v[100:103], v[206:209], v[182:185], v[100:103]
	v_mfma_f32_16x16x32_bf16 v[96:99], v[214:217], v[182:185], v[96:99]
	v_mfma_f32_16x16x32_bf16 v[84:87], v[206:209], v[190:193], v[84:87]
	v_mfma_f32_16x16x32_bf16 v[80:83], v[214:217], v[190:193], v[80:83]
	v_mfma_f32_16x16x32_bf16 v[68:71], v[206:209], v[198:201], v[68:71]
	v_mfma_f32_16x16x32_bf16 v[64:67], v[214:217], v[198:201], v[64:67]
	v_mfma_f32_16x16x32_bf16 v[116:119], v[210:213], v[178:181], v[116:119]
	v_mfma_f32_16x16x32_bf16 v[112:115], v[218:221], v[178:181], v[112:115]
	v_mfma_f32_16x16x32_bf16 v[100:103], v[210:213], v[186:189], v[100:103]
	v_mfma_f32_16x16x32_bf16 v[96:99], v[218:221], v[186:189], v[96:99]
	v_mfma_f32_16x16x32_bf16 v[84:87], v[210:213], v[194:197], v[84:87]
	v_mfma_f32_16x16x32_bf16 v[80:83], v[218:221], v[194:197], v[80:83]
	v_mfma_f32_16x16x32_bf16 v[68:71], v[210:213], v[202:205], v[68:71]
	v_mfma_f32_16x16x32_bf16 v[64:67], v[218:221], v[202:205], v[64:67]
	s_setprio 0
	s_mov_b32 m0, s42
	v_lshl_add_u64 v[174:175], v[224:225], 0, s[10:11]
	s_barrier
	ds_read_b128 v[170:173], v155 offset:49152
	ds_read_b128 v[178:181], v155 offset:50176
	ds_read_b128 v[182:185], v155 offset:51200
	ds_read_b128 v[186:189], v155 offset:52224
	ds_read_b128 v[190:193], v155 offset:53248
	ds_read_b128 v[194:197], v155 offset:54272
	ds_read_b128 v[198:201], v155 offset:55296
	ds_read_b128 v[202:205], v155 offset:56320
	global_load_lds_dwordx4 v[174:175], off
	v_lshl_add_u64 v[174:175], v[226:227], 0, s[10:11]
	s_mov_b32 m0, s43
	s_nop 0
	global_load_lds_dwordx4 v[174:175], off
	s_barrier
; __device__ __forceinline__ unsigned pk2(float lo, float hi) { f32x2 v; v.x = lo; v.y = hi; return __builtin_bit_cast(unsigned, __builtin_convertvector(v, hwbf2)); }
; #define PG8_STAGE(bufoff, gbase, voff) do { _Pragma("unroll") for (int _i = 0; _i < 2; ++_i) \
;         __builtin_amdgcn_global_load_lds((const unsigned*)((const char*)(gbase) + (voff)[_i]), (LAS unsigned*)(lds + (bufoff) + ldsw + _i * 8192), 16, 0, 0); } while (0)
; #define PG8_MMA(ai, bj, At, Bt) do { __builtin_amdgcn_s_setprio(1); _Pragma("unroll") for (int m = 0; m < 4; ++m) _Pragma("unroll") for (int n = 0; n < 2; ++n) _Pragma("unroll") for (int k = 0; k < 2; ++k) \
;         acc[ai][bj][m][n] = __builtin_amdgcn_mfma_f32_16x16x32_bf16(Bt[n][k], At[m][k], acc[ai][bj][m][n], 0, 0, 0); __builtin_amdgcn_s_setprio(0); } while (0)
; #define PG8_WAIT_V(n) asm volatile("s_waitcnt vmcnt(" #n ")" ::: "memory")
; #define PG8_WAIT_L(n) asm volatile("s_waitcnt lgkmcnt(" #n ")" ::: "memory")
; #define PG8_BAR __builtin_amdgcn_s_barrier()
; #define PG8_SCHED __builtin_amdgcn_sched_barrier(0)
; template <class Epi>
; __device__ __forceinline__ void gemm_phase(LAS unsigned char* lds, const Gemm g, const StaticOrder& S, const Epi& E) {
;     ...
;             PG8_BAR; PG8_WAIT_L(0); PG8_MMA(1, 0, At, B0); PG8_BAR; PG8_SCHED;
;             PG8_STAGE(PG8_SB(1, 1), b3 + hstepB, voffB);
;             PG8_WAIT_V(6); PG8_BAR; PG8_MMA(1, 1, At, B1); PG8_BAR;
;         }
;     __device__ __forceinline__ void operator()(const f32x4 (&acc)[2][2][4][2], const pg8::Unit& u, int wr, int wc, int fr, int fq) const {
;     ...
;             for (int m = 0; m < 4; ++m) { const int row = row0 + ai * 128 + m * 16; bf16_t* rowp = O + (size_t)row * ldc + col0; float ss = 0.f;
; #pragma unroll
;                 for (int bj = 0; bj < 2; ++bj) { const f32x4 v0 = acc[ai][bj][m][0], v1 = acc[ai][bj][m][1];
;                     ss += (v0[0] * v0[0] + v0[1] * v0[1]) + (v0[2] * v0[2] + v0[3] * v0[3]) + (v1[0] * v1[0] + v1[1] * v1[1]) + (v1[2] * v1[2] + v1[3] * v1[3]);
;                     u32x4 w; w.x = pk2(v0[0], v0[1]); w.y = pk2(v0[2], v0[3]); w.z = pk2(v1[0], v1[1]); w.w = pk2(v1[2], v1[3]);
;                     *(u32x4*)(rowp + bj * 128) = w; }
;                 ss += __shfl_xor(ss, 16); ss += __shfl_xor(ss, 32);
;                 if (fq == 0) atomicAdd(sumsq + row, ss); }
	s_waitcnt lgkmcnt(0)
	s_setprio 1
	s_waitcnt lgkmcnt(0)
	v_mfma_f32_16x16x32_bf16 v[60:63], v[144:147], v[170:173], v[60:63]
	v_mfma_f32_16x16x32_bf16 v[56:59], v[162:165], v[170:173], v[56:59]
	v_mfma_f32_16x16x32_bf16 v[44:47], v[144:147], v[182:185], v[44:47]
	v_mfma_f32_16x16x32_bf16 v[40:43], v[162:165], v[182:185], v[40:43]
	v_mfma_f32_16x16x32_bf16 v[28:31], v[144:147], v[190:193], v[28:31]
	v_mfma_f32_16x16x32_bf16 v[24:27], v[162:165], v[190:193], v[24:27]
	v_mfma_f32_16x16x32_bf16 v[12:15], v[144:147], v[198:201], v[12:15]
	v_mfma_f32_16x16x32_bf16 v[8:11], v[162:165], v[198:201], v[8:11]
	v_mfma_f32_16x16x32_bf16 v[60:63], v[158:161], v[178:181], v[60:63]
	v_mfma_f32_16x16x32_bf16 v[56:59], v[166:169], v[178:181], v[56:59]
	v_mfma_f32_16x16x32_bf16 v[44:47], v[158:161], v[186:189], v[44:47]
	v_mfma_f32_16x16x32_bf16 v[40:43], v[166:169], v[186:189], v[40:43]
	v_mfma_f32_16x16x32_bf16 v[28:31], v[158:161], v[194:197], v[28:31]
	v_mfma_f32_16x16x32_bf16 v[24:27], v[166:169], v[194:197], v[24:27]
	v_mfma_f32_16x16x32_bf16 v[12:15], v[158:161], v[202:205], v[12:15]
	v_mfma_f32_16x16x32_bf16 v[8:11], v[166:169], v[202:205], v[8:11]
	s_setprio 0
	s_barrier
	s_add_u32 s36, s36, 0x40080
	s_addc_u32 s37, s37, 0
	s_add_i32 s38, s38, s28
	v_lshl_add_u64 v[144:145], s[36:37], 0, v[130:131]
	s_mov_b32 m0, s38
	s_nop 0
	global_load_lds_dwordx4 v[144:145], off
	v_lshl_add_u64 v[144:145], s[36:37], 0, v[134:135]
	s_add_i32 m0, s38, 0x2000
	s_nop 0
	global_load_lds_dwordx4 v[144:145], off
	s_waitcnt vmcnt(6)
	s_barrier
	s_setprio 1
	v_mfma_f32_16x16x32_bf16 v[52:55], v[206:209], v[170:173], v[52:55]
	v_mfma_f32_16x16x32_bf16 v[48:51], v[214:217], v[170:173], v[48:51]
	v_mfma_f32_16x16x32_bf16 v[36:39], v[206:209], v[182:185], v[36:39]
	v_mfma_f32_16x16x32_bf16 v[32:35], v[214:217], v[182:185], v[32:35]
	v_mfma_f32_16x16x32_bf16 v[20:23], v[206:209], v[190:193], v[20:23]
	v_mfma_f32_16x16x32_bf16 v[16:19], v[214:217], v[190:193], v[16:19]
	v_mfma_f32_16x16x32_bf16 v[4:7], v[206:209], v[198:201], v[4:7]
	v_mfma_f32_16x16x32_bf16 v[0:3], v[214:217], v[198:201], v[0:3]
	v_mfma_f32_16x16x32_bf16 v[52:55], v[210:213], v[178:181], v[52:55]
	v_mfma_f32_16x16x32_bf16 v[48:51], v[218:221], v[178:181], v[48:51]
	v_mfma_f32_16x16x32_bf16 v[36:39], v[210:213], v[186:189], v[36:39]
	v_mfma_f32_16x16x32_bf16 v[32:35], v[218:221], v[186:189], v[32:35]
	v_mfma_f32_16x16x32_bf16 v[20:23], v[210:213], v[194:197], v[20:23]
	v_mfma_f32_16x16x32_bf16 v[16:19], v[218:221], v[194:197], v[16:19]
	v_mfma_f32_16x16x32_bf16 v[4:7], v[210:213], v[202:205], v[4:7]
	v_mfma_f32_16x16x32_bf16 v[0:3], v[218:221], v[202:205], v[0:3]
	s_setprio 0
	s_add_i32 s52, s52, 2
	s_add_u32 s34, s34, 0x100
	s_addc_u32 s35, s35, 0
	s_add_u32 s50, s50, 0x100
	s_addc_u32 s51, s51, 0
	s_cmp_gt_u32 s52, 13
	s_barrier
	s_cbranch_scc0 .LBB0_967
	v_mul_f32_e32 v162, v125, v125
	v_mul_f32_e32 v163, v127, v127
	v_fmac_f32_e32 v162, v124, v124
	v_fmac_f32_e32 v163, v126, v126
	v_cvt_pk_bf16_f32 v124, v124, v125
	v_cvt_pk_bf16_f32 v125, v126, v127
	v_mul_f32_e32 v126, v117, v117
	v_mul_f32_e32 v127, v119, v119
	v_fmac_f32_e32 v126, v116, v116
	v_fmac_f32_e32 v127, v118, v118
	v_add_f32_e32 v162, v162, v163
	v_mul_f32_e32 v163, v121, v121
	v_add_f32_e32 v126, v126, v127
	v_mul_f32_e32 v127, v113, v113
	v_and_b32_e32 v158, 64, v157
	v_fmac_f32_e32 v163, v120, v120
	v_fmac_f32_e32 v127, v112, v112
	v_xor_b32_e32 v147, 16, v157
	v_add_u32_e32 v158, 64, v158
	v_add_f32_e32 v162, v162, v163
	v_mul_f32_e32 v163, v123, v123
	v_add_f32_e32 v126, v126, v127
	v_mul_f32_e32 v127, v115, v115
	v_cmp_lt_i32_e32 vcc, v147, v158
	v_fmac_f32_e32 v163, v122, v122
	v_fmac_f32_e32 v127, v114, v114
	v_cndmask_b32_e32 v147, v157, v147, vcc
	v_add_f32_e32 v162, v163, v162
	v_add_f32_e32 v126, v127, v126
	v_lshlrev_b32_e32 v159, 2, v147
	v_add_f32_e32 v162, v162, v126
	v_mov_b32_e32 v163, v162
	s_nop 1
	v_permlane16_swap_b32_e32 v162, v163
	v_xor_b32_e32 v147, 32, v157
	v_cmp_lt_i32_e32 vcc, v147, v158
	v_cvt_pk_bf16_f32 v126, v120, v121
	v_cvt_pk_bf16_f32 v120, v116, v117
	v_cndmask_b32_e32 v147, v157, v147, vcc
	v_lshlrev_b32_e32 v158, 2, v147
	s_waitcnt lgkmcnt(0)
	v_add_f32_e32 v116, v162, v163
	v_lshl_add_u32 v146, s24, 8, v151
	v_mov_b32_e32 v117, v116
	s_nop 1
	v_permlane32_swap_b32_e32 v116, v117
	v_ashrrev_i32_e32 v147, 31, v146
	v_lshl_or_b32 v144, s30, 8, v153
	v_lshlrev_b64 v[160:161], 11, v[146:147]
	v_ashrrev_i32_e32 v145, 31, v144
	v_lshl_add_u64 v[160:161], s[6:7], 0, v[160:161]
	v_lshl_add_u64 v[160:161], v[144:145], 1, v[160:161]
	v_cvt_pk_bf16_f32 v127, v122, v123
	v_cvt_pk_bf16_f32 v121, v118, v119
	v_cvt_pk_bf16_f32 v122, v112, v113
	v_cvt_pk_bf16_f32 v123, v114, v115
	global_store_dwordx4 v[160:161], v[124:127], off
	global_store_dwordx4 v[160:161], v[120:123], off offset:256
	s_and_saveexec_b64 s[24:25], s[0:1]
	s_cbranch_execz .LBB0_970
	v_lshl_add_u64 v[112:113], v[146:147], 2, s[8:9]
	s_waitcnt lgkmcnt(0)
	v_add_f32_e32 v114, v116, v117
	global_atomic_add_f32 v[112:113], v114, off
; __device__ __forceinline__ unsigned pk2(float lo, float hi) { f32x2 v; v.x = lo; v.y = hi; return __builtin_bit_cast(unsigned, __builtin_convertvector(v, hwbf2)); }
;     __device__ __forceinline__ void operator()(const f32x4 (&acc)[2][2][4][2], const pg8::Unit& u, int wr, int wc, int fr, int fq) const {
;     ...
;             for (int m = 0; m < 4; ++m) { const int row = row0 + ai * 128 + m * 16; bf16_t* rowp = O + (size_t)row * ldc + col0; float ss = 0.f;
; #pragma unroll
;                 for (int bj = 0; bj < 2; ++bj) { const f32x4 v0 = acc[ai][bj][m][0], v1 = acc[ai][bj][m][1];
;                     ss += (v0[0] * v0[0] + v0[1] * v0[1]) + (v0[2] * v0[2] + v0[3] * v0[3]) + (v1[0] * v1[0] + v1[1] * v1[1]) + (v1[2] * v1[2] + v1[3] * v1[3]);
;                     u32x4 w; w.x = pk2(v0[0], v0[1]); w.y = pk2(v0[2], v0[3]); w.z = pk2(v1[0], v1[1]); w.w = pk2(v1[2], v1[3]);
;                     *(u32x4*)(rowp + bj * 128) = w; }
;                 ss += __shfl_xor(ss, 16); ss += __shfl_xor(ss, 32);
;                 if (fq == 0) atomicAdd(sumsq + row, ss); }
.LBB0_970:
	s_or_b64 exec, exec, s[24:25]
	v_mul_f32_e32 v116, v109, v109
	s_waitcnt lgkmcnt(0)
	v_mul_f32_e32 v117, v111, v111
	v_fmac_f32_e32 v116, v108, v108
	v_fmac_f32_e32 v117, v110, v110
	v_cvt_pk_bf16_f32 v108, v108, v109
	v_cvt_pk_bf16_f32 v109, v110, v111
	v_mul_f32_e32 v110, v101, v101
	v_mul_f32_e32 v111, v103, v103
	v_fmac_f32_e32 v110, v100, v100
	v_fmac_f32_e32 v111, v102, v102
	v_add_f32_e32 v116, v116, v117
	v_mul_f32_e32 v117, v105, v105
	v_add_f32_e32 v110, v110, v111
	v_mul_f32_e32 v111, v97, v97
	v_fmac_f32_e32 v117, v104, v104
	v_fmac_f32_e32 v111, v96, v96
	v_add_f32_e32 v116, v116, v117
	v_mul_f32_e32 v117, v107, v107
	v_add_f32_e32 v110, v110, v111
	v_mul_f32_e32 v111, v99, v99
	v_fmac_f32_e32 v117, v106, v106
	v_fmac_f32_e32 v111, v98, v98
	v_add_f32_e32 v116, v117, v116
	v_add_f32_e32 v110, v111, v110
	v_add_f32_e32 v116, v116, v110
	v_mov_b32_e32 v117, v116
	s_nop 1
	v_permlane16_swap_b32_e32 v116, v117
	v_cvt_pk_bf16_f32 v110, v104, v105
	v_cvt_pk_bf16_f32 v104, v100, v101
	v_or_b32_e32 v112, 16, v146
	v_ashrrev_i32_e32 v113, 31, v112
	s_waitcnt lgkmcnt(0)
	v_add_f32_e32 v100, v116, v117
	v_mov_b32_e32 v101, v100
	s_nop 1
	v_permlane32_swap_b32_e32 v100, v101
	v_lshlrev_b64 v[114:115], 11, v[112:113]
	v_lshl_add_u64 v[114:115], s[6:7], 0, v[114:115]
	v_lshl_add_u64 v[114:115], v[144:145], 1, v[114:115]
	v_cvt_pk_bf16_f32 v111, v106, v107
	v_cvt_pk_bf16_f32 v105, v102, v103
	v_cvt_pk_bf16_f32 v106, v96, v97
	v_cvt_pk_bf16_f32 v107, v98, v99
	global_store_dwordx4 v[114:115], v[108:111], off
	global_store_dwordx4 v[114:115], v[104:107], off offset:256
	s_and_saveexec_b64 s[24:25], s[0:1]
	s_cbranch_execz .LBB0_972
	v_lshl_add_u64 v[96:97], v[112:113], 2, s[8:9]
	s_waitcnt lgkmcnt(0)
	v_add_f32_e32 v98, v100, v101
	global_atomic_add_f32 v[96:97], v98, off
.LBB0_972:
	s_or_b64 exec, exec, s[24:25]
	v_mul_f32_e32 v100, v93, v93
	s_waitcnt lgkmcnt(0)
	v_mul_f32_e32 v101, v95, v95
	v_fmac_f32_e32 v100, v92, v92
	v_fmac_f32_e32 v101, v94, v94
	v_cvt_pk_bf16_f32 v92, v92, v93
	v_cvt_pk_bf16_f32 v93, v94, v95
	v_mul_f32_e32 v94, v85, v85
	v_mul_f32_e32 v95, v87, v87
	v_fmac_f32_e32 v94, v84, v84
	v_fmac_f32_e32 v95, v86, v86
	v_add_f32_e32 v100, v100, v101
	v_mul_f32_e32 v101, v89, v89
	v_add_f32_e32 v94, v94, v95
	v_mul_f32_e32 v95, v81, v81
	v_fmac_f32_e32 v101, v88, v88
	v_fmac_f32_e32 v95, v80, v80
	v_add_f32_e32 v100, v100, v101
	v_mul_f32_e32 v101, v91, v91
	v_add_f32_e32 v94, v94, v95
	v_mul_f32_e32 v95, v83, v83
	v_fmac_f32_e32 v101, v90, v90
	v_fmac_f32_e32 v95, v82, v82
	v_add_f32_e32 v100, v101, v100
	v_add_f32_e32 v94, v95, v94
	v_add_f32_e32 v100, v100, v94
	v_mov_b32_e32 v101, v100
	s_nop 1
	v_permlane16_swap_b32_e32 v100, v101
	v_cvt_pk_bf16_f32 v94, v88, v89
	v_cvt_pk_bf16_f32 v88, v84, v85
	v_or_b32_e32 v96, 32, v146
	v_ashrrev_i32_e32 v97, 31, v96
	s_waitcnt lgkmcnt(0)
	v_add_f32_e32 v84, v100, v101
	v_mov_b32_e32 v85, v84
	s_nop 1
	v_permlane32_swap_b32_e32 v84, v85
	v_lshlrev_b64 v[98:99], 11, v[96:97]
	v_lshl_add_u64 v[98:99], s[6:7], 0, v[98:99]
	v_lshl_add_u64 v[98:99], v[144:145], 1, v[98:99]
	v_cvt_pk_bf16_f32 v95, v90, v91
	v_cvt_pk_bf16_f32 v89, v86, v87
	v_cvt_pk_bf16_f32 v90, v80, v81
	v_cvt_pk_bf16_f32 v91, v82, v83
	global_store_dwordx4 v[98:99], v[92:95], off
	global_store_dwordx4 v[98:99], v[88:91], off offset:256
	s_and_saveexec_b64 s[24:25], s[0:1]
	s_cbranch_execz .LBB0_974
	v_lshl_add_u64 v[80:81], v[96:97], 2, s[8:9]
	s_waitcnt lgkmcnt(0)
	v_add_f32_e32 v82, v84, v85
	global_atomic_add_f32 v[80:81], v82, off
.LBB0_974:
	s_or_b64 exec, exec, s[24:25]
	v_mul_f32_e32 v84, v77, v77
	s_waitcnt lgkmcnt(0)
	v_mul_f32_e32 v85, v79, v79
	v_fmac_f32_e32 v84, v76, v76
	v_fmac_f32_e32 v85, v78, v78
	v_cvt_pk_bf16_f32 v76, v76, v77
	v_cvt_pk_bf16_f32 v77, v78, v79
	v_mul_f32_e32 v78, v69, v69
	v_mul_f32_e32 v79, v71, v71
	v_fmac_f32_e32 v78, v68, v68
	v_fmac_f32_e32 v79, v70, v70
	v_add_f32_e32 v84, v84, v85
	v_mul_f32_e32 v85, v73, v73
	v_add_f32_e32 v78, v78, v79
	v_mul_f32_e32 v79, v65, v65
	v_fmac_f32_e32 v85, v72, v72
	v_fmac_f32_e32 v79, v64, v64
	v_add_f32_e32 v84, v84, v85
	v_mul_f32_e32 v85, v75, v75
	v_add_f32_e32 v78, v78, v79
	v_mul_f32_e32 v79, v67, v67
	v_fmac_f32_e32 v85, v74, v74
	v_fmac_f32_e32 v79, v66, v66
	v_add_f32_e32 v84, v85, v84
	v_add_f32_e32 v78, v79, v78
	v_add_f32_e32 v84, v84, v78
	v_mov_b32_e32 v85, v84
	s_nop 1
	v_permlane16_swap_b32_e32 v84, v85
	v_cvt_pk_bf16_f32 v78, v72, v73
	v_cvt_pk_bf16_f32 v72, v68, v69
	v_or_b32_e32 v80, 48, v146
	v_ashrrev_i32_e32 v81, 31, v80
	s_waitcnt lgkmcnt(0)
	v_add_f32_e32 v68, v84, v85
	v_mov_b32_e32 v69, v68
	s_nop 1
	v_permlane32_swap_b32_e32 v68, v69
	v_lshlrev_b64 v[82:83], 11, v[80:81]
	v_lshl_add_u64 v[82:83], s[6:7], 0, v[82:83]
	v_lshl_add_u64 v[82:83], v[144:145], 1, v[82:83]
	v_cvt_pk_bf16_f32 v79, v74, v75
	v_cvt_pk_bf16_f32 v73, v70, v71
	v_cvt_pk_bf16_f32 v74, v64, v65
	v_cvt_pk_bf16_f32 v75, v66, v67
	global_store_dwordx4 v[82:83], v[76:79], off
	global_store_dwordx4 v[82:83], v[72:75], off offset:256
	s_and_saveexec_b64 s[24:25], s[0:1]
	s_cbranch_execz .LBB0_976
	v_lshl_add_u64 v[64:65], v[80:81], 2, s[8:9]
	s_waitcnt lgkmcnt(0)
	v_add_f32_e32 v66, v68, v69
	global_atomic_add_f32 v[64:65], v66, off
; __device__ __forceinline__ unsigned pk2(float lo, float hi) { f32x2 v; v.x = lo; v.y = hi; return __builtin_bit_cast(unsigned, __builtin_convertvector(v, hwbf2)); }
;     __device__ __forceinline__ void operator()(const f32x4 (&acc)[2][2][4][2], const pg8::Unit& u, int wr, int wc, int fr, int fq) const {
;     ...
;             for (int m = 0; m < 4; ++m) { const int row = row0 + ai * 128 + m * 16; bf16_t* rowp = O + (size_t)row * ldc + col0; float ss = 0.f;
; #pragma unroll
;                 for (int bj = 0; bj < 2; ++bj) { const f32x4 v0 = acc[ai][bj][m][0], v1 = acc[ai][bj][m][1];
;                     ss += (v0[0] * v0[0] + v0[1] * v0[1]) + (v0[2] * v0[2] + v0[3] * v0[3]) + (v1[0] * v1[0] + v1[1] * v1[1]) + (v1[2] * v1[2] + v1[3] * v1[3]);
;                     u32x4 w; w.x = pk2(v0[0], v0[1]); w.y = pk2(v0[2], v0[3]); w.z = pk2(v1[0], v1[1]); w.w = pk2(v1[2], v1[3]);
;                     *(u32x4*)(rowp + bj * 128) = w; }
;                 ss += __shfl_xor(ss, 16); ss += __shfl_xor(ss, 32);
;                 if (fq == 0) atomicAdd(sumsq + row, ss); }
.LBB0_976:
	s_or_b64 exec, exec, s[24:25]
	v_mul_f32_e32 v68, v61, v61
	s_waitcnt lgkmcnt(0)
	v_mul_f32_e32 v69, v63, v63
	v_fmac_f32_e32 v68, v60, v60
	v_fmac_f32_e32 v69, v62, v62
	v_cvt_pk_bf16_f32 v60, v60, v61
	v_cvt_pk_bf16_f32 v61, v62, v63
	v_mul_f32_e32 v62, v53, v53
	v_mul_f32_e32 v63, v55, v55
	v_fmac_f32_e32 v62, v52, v52
	v_fmac_f32_e32 v63, v54, v54
	v_add_f32_e32 v68, v68, v69
	v_mul_f32_e32 v69, v57, v57
	v_add_f32_e32 v62, v62, v63
	v_mul_f32_e32 v63, v49, v49
	v_fmac_f32_e32 v69, v56, v56
	v_fmac_f32_e32 v63, v48, v48
	v_add_f32_e32 v68, v68, v69
	v_mul_f32_e32 v69, v59, v59
	v_add_f32_e32 v62, v62, v63
	v_mul_f32_e32 v63, v51, v51
	v_fmac_f32_e32 v69, v58, v58
	v_fmac_f32_e32 v63, v50, v50
	v_add_f32_e32 v68, v69, v68
	v_add_f32_e32 v62, v63, v62
	v_add_f32_e32 v68, v68, v62
	v_mov_b32_e32 v69, v68
	s_nop 1
	v_permlane16_swap_b32_e32 v68, v69
	v_cvt_pk_bf16_f32 v62, v56, v57
	v_cvt_pk_bf16_f32 v56, v52, v53
	v_add_u32_e32 v64, 0x80, v146
	v_ashrrev_i32_e32 v65, 31, v64
	s_waitcnt lgkmcnt(0)
	v_add_f32_e32 v52, v68, v69
	v_mov_b32_e32 v53, v52
	s_nop 1
	v_permlane32_swap_b32_e32 v52, v53
	v_lshlrev_b64 v[66:67], 11, v[64:65]
	v_lshl_add_u64 v[66:67], s[6:7], 0, v[66:67]
	v_lshl_add_u64 v[66:67], v[144:145], 1, v[66:67]
	v_cvt_pk_bf16_f32 v63, v58, v59
	v_cvt_pk_bf16_f32 v57, v54, v55
	v_cvt_pk_bf16_f32 v58, v48, v49
	v_cvt_pk_bf16_f32 v59, v50, v51
	global_store_dwordx4 v[66:67], v[60:63], off
	global_store_dwordx4 v[66:67], v[56:59], off offset:256
	s_and_saveexec_b64 s[24:25], s[0:1]
	s_cbranch_execz .LBB0_978
	v_lshl_add_u64 v[48:49], v[64:65], 2, s[8:9]
	s_waitcnt lgkmcnt(0)
	v_add_f32_e32 v50, v52, v53
	global_atomic_add_f32 v[48:49], v50, off
.LBB0_978:
	s_or_b64 exec, exec, s[24:25]
	v_mul_f32_e32 v52, v45, v45
	s_waitcnt lgkmcnt(0)
	v_mul_f32_e32 v53, v47, v47
	v_fmac_f32_e32 v52, v44, v44
	v_fmac_f32_e32 v53, v46, v46
	v_cvt_pk_bf16_f32 v44, v44, v45
	v_cvt_pk_bf16_f32 v45, v46, v47
	v_mul_f32_e32 v46, v37, v37
	v_mul_f32_e32 v47, v39, v39
	v_fmac_f32_e32 v46, v36, v36
	v_fmac_f32_e32 v47, v38, v38
	v_add_f32_e32 v52, v52, v53
	v_mul_f32_e32 v53, v41, v41
	v_add_f32_e32 v46, v46, v47
	v_mul_f32_e32 v47, v33, v33
	v_fmac_f32_e32 v53, v40, v40
	v_fmac_f32_e32 v47, v32, v32
	v_add_f32_e32 v52, v52, v53
	v_mul_f32_e32 v53, v43, v43
	v_add_f32_e32 v46, v46, v47
	v_mul_f32_e32 v47, v35, v35
	v_fmac_f32_e32 v53, v42, v42
	v_fmac_f32_e32 v47, v34, v34
	v_add_f32_e32 v52, v53, v52
	v_add_f32_e32 v46, v47, v46
	v_add_f32_e32 v52, v52, v46
	v_mov_b32_e32 v53, v52
	s_nop 1
	v_permlane16_swap_b32_e32 v52, v53
	v_cvt_pk_bf16_f32 v46, v40, v41
	v_cvt_pk_bf16_f32 v40, v36, v37
	v_add_u32_e32 v48, 0x90, v146
	v_ashrrev_i32_e32 v49, 31, v48
	s_waitcnt lgkmcnt(0)
	v_add_f32_e32 v36, v52, v53
	v_mov_b32_e32 v37, v36
	s_nop 1
	v_permlane32_swap_b32_e32 v36, v37
	v_lshlrev_b64 v[50:51], 11, v[48:49]
	v_lshl_add_u64 v[50:51], s[6:7], 0, v[50:51]
	v_lshl_add_u64 v[50:51], v[144:145], 1, v[50:51]
	v_cvt_pk_bf16_f32 v47, v42, v43
	v_cvt_pk_bf16_f32 v41, v38, v39
	v_cvt_pk_bf16_f32 v42, v32, v33
	v_cvt_pk_bf16_f32 v43, v34, v35
	global_store_dwordx4 v[50:51], v[44:47], off
	global_store_dwordx4 v[50:51], v[40:43], off offset:256
	s_and_saveexec_b64 s[24:25], s[0:1]
	s_cbranch_execz .LBB0_980
	v_lshl_add_u64 v[32:33], v[48:49], 2, s[8:9]
	s_waitcnt lgkmcnt(0)
	v_add_f32_e32 v34, v36, v37
	global_atomic_add_f32 v[32:33], v34, off
.LBB0_980:
	s_or_b64 exec, exec, s[24:25]
	v_mul_f32_e32 v36, v29, v29
	s_waitcnt lgkmcnt(0)
	v_mul_f32_e32 v37, v31, v31
	v_fmac_f32_e32 v36, v28, v28
	v_fmac_f32_e32 v37, v30, v30
	v_cvt_pk_bf16_f32 v28, v28, v29
	v_cvt_pk_bf16_f32 v29, v30, v31
	v_mul_f32_e32 v30, v21, v21
	v_mul_f32_e32 v31, v23, v23
	v_fmac_f32_e32 v30, v20, v20
	v_fmac_f32_e32 v31, v22, v22
	v_add_f32_e32 v36, v36, v37
	v_mul_f32_e32 v37, v25, v25
	v_add_f32_e32 v30, v30, v31
	v_mul_f32_e32 v31, v17, v17
	v_fmac_f32_e32 v37, v24, v24
	v_fmac_f32_e32 v31, v16, v16
	v_add_f32_e32 v36, v36, v37
	v_mul_f32_e32 v37, v27, v27
	v_add_f32_e32 v30, v30, v31
	v_mul_f32_e32 v31, v19, v19
	v_fmac_f32_e32 v37, v26, v26
	v_fmac_f32_e32 v31, v18, v18
	v_add_f32_e32 v36, v37, v36
	v_add_f32_e32 v30, v31, v30
	v_add_f32_e32 v36, v36, v30
	v_mov_b32_e32 v37, v36
	s_nop 1
	v_permlane16_swap_b32_e32 v36, v37
	v_cvt_pk_bf16_f32 v30, v24, v25
	v_cvt_pk_bf16_f32 v24, v20, v21
	v_add_u32_e32 v32, 0xa0, v146
	v_ashrrev_i32_e32 v33, 31, v32
	s_waitcnt lgkmcnt(0)
	v_add_f32_e32 v20, v36, v37
	v_mov_b32_e32 v21, v20
	s_nop 1
	v_permlane32_swap_b32_e32 v20, v21
	v_lshlrev_b64 v[34:35], 11, v[32:33]
	v_lshl_add_u64 v[34:35], s[6:7], 0, v[34:35]
	v_lshl_add_u64 v[34:35], v[144:145], 1, v[34:35]
	v_cvt_pk_bf16_f32 v31, v26, v27
	v_cvt_pk_bf16_f32 v25, v22, v23
	v_cvt_pk_bf16_f32 v26, v16, v17
	v_cvt_pk_bf16_f32 v27, v18, v19
	global_store_dwordx4 v[34:35], v[28:31], off
	global_store_dwordx4 v[34:35], v[24:27], off offset:256
	s_and_saveexec_b64 s[24:25], s[0:1]
	s_cbranch_execz .LBB0_982
	v_lshl_add_u64 v[16:17], v[32:33], 2, s[8:9]
	s_waitcnt lgkmcnt(0)
	v_add_f32_e32 v18, v20, v21
	global_atomic_add_f32 v[16:17], v18, off
.LBB0_982:
	s_or_b64 exec, exec, s[24:25]
	v_mul_f32_e32 v20, v13, v13
	s_waitcnt lgkmcnt(0)
	v_mul_f32_e32 v21, v15, v15
	v_fmac_f32_e32 v20, v12, v12
	v_fmac_f32_e32 v21, v14, v14
	v_cvt_pk_bf16_f32 v12, v12, v13
	v_cvt_pk_bf16_f32 v13, v14, v15
	v_mul_f32_e32 v14, v5, v5
	v_mul_f32_e32 v15, v7, v7
	v_fmac_f32_e32 v14, v4, v4
	v_fmac_f32_e32 v15, v6, v6
	v_add_f32_e32 v20, v20, v21
	v_mul_f32_e32 v21, v9, v9
	v_add_f32_e32 v14, v14, v15
	v_mul_f32_e32 v15, v1, v1
	v_fmac_f32_e32 v21, v8, v8
	v_fmac_f32_e32 v15, v0, v0
	v_add_f32_e32 v20, v20, v21
	v_mul_f32_e32 v21, v11, v11
	v_add_f32_e32 v14, v14, v15
	v_mul_f32_e32 v15, v3, v3
	v_fmac_f32_e32 v21, v10, v10
	v_fmac_f32_e32 v15, v2, v2
	v_add_f32_e32 v20, v21, v20
	v_add_f32_e32 v14, v15, v14
	v_add_f32_e32 v20, v20, v14
	v_mov_b32_e32 v21, v20
	s_nop 1
	v_permlane16_swap_b32_e32 v20, v21
	v_cvt_pk_bf16_f32 v14, v8, v9
	v_cvt_pk_bf16_f32 v8, v4, v5
	v_add_u32_e32 v16, 0xb0, v146
	v_ashrrev_i32_e32 v17, 31, v16
	s_waitcnt lgkmcnt(0)
	v_add_f32_e32 v4, v20, v21
	v_mov_b32_e32 v5, v4
	s_nop 1
	v_permlane32_swap_b32_e32 v4, v5
	v_lshlrev_b64 v[18:19], 11, v[16:17]
	v_lshl_add_u64 v[18:19], s[6:7], 0, v[18:19]
	v_lshl_add_u64 v[18:19], v[144:145], 1, v[18:19]
	v_cvt_pk_bf16_f32 v15, v10, v11
	v_cvt_pk_bf16_f32 v9, v6, v7
	v_cvt_pk_bf16_f32 v10, v0, v1
	v_cvt_pk_bf16_f32 v11, v2, v3
	global_store_dwordx4 v[18:19], v[12:15], off
	global_store_dwordx4 v[18:19], v[8:11], off offset:256
	s_and_saveexec_b64 s[24:25], s[0:1]
	s_cbranch_execz .LBB0_959
	v_lshl_add_u64 v[0:1], v[16:17], 2, s[8:9]
	s_waitcnt lgkmcnt(0)
	v_add_f32_e32 v2, v4, v5
	global_atomic_add_f32 v[0:1], v2, off
	s_branch .LBB0_959

; #define PG8_STAGE(bufoff, gbase, voff) do { _Pragma("unroll") for (int _i = 0; _i < 2; ++_i) \
;         __builtin_amdgcn_global_load_lds((const unsigned*)((const char*)(gbase) + (voff)[_i]), (LAS unsigned*)(lds + (bufoff) + ldsw + _i * 8192), 16, 0, 0); } while (0)
; #define PG8_LDA(dst, b, h) do { _Pragma("unroll") for (int m = 0; m < 4; ++m) _Pragma("unroll") for (int k = 0; k < 2; ++k) dst[m][k] = *(const LAS bf16x8*)(lds + PG8_SA(b, h) + aoff + m * 2048 + k * 1024); } while (0)
; #define PG8_LDB(dst, b, h) do { _Pragma("unroll") for (int n = 0; n < 2; ++n) _Pragma("unroll") for (int k = 0; k < 2; ++k) dst[n][k] = *(const LAS bf16x8*)(lds + PG8_SB(b, h) + boff + n * 2048 + k * 1024); } while (0)
; #define PG8_MMA(ai, bj, At, Bt) do { __builtin_amdgcn_s_setprio(1); _Pragma("unroll") for (int m = 0; m < 4; ++m) _Pragma("unroll") for (int n = 0; n < 2; ++n) _Pragma("unroll") for (int k = 0; k < 2; ++k) \
;         acc[ai][bj][m][n] = __builtin_amdgcn_mfma_f32_16x16x32_bf16(Bt[n][k], At[m][k], acc[ai][bj][m][n], 0, 0, 0); __builtin_amdgcn_s_setprio(0); } while (0)
; #define PG8_WAIT_L(n) asm volatile("s_waitcnt lgkmcnt(" #n ")" ::: "memory")
; #define PG8_BAR __builtin_amdgcn_s_barrier()
; #define PG8_SCHED __builtin_amdgcn_sched_barrier(0)
; template <class Epi>
; __device__ __forceinline__ void gemm_phase(LAS unsigned char* lds, const Gemm g, const StaticOrder& S, const Epi& E) {
;     ...
;             PG8_LDB(B0, 0, 0); PG8_SCHED; PG8_LDA(At, 0, 0); PG8_STAGE(PG8_SA(1, 1), a1 + hstepA, voffA);
;             PG8_WAIT_L(8); PG8_BAR; PG8_WAIT_L(0); PG8_MMA(0, 0, At, B0); PG8_BAR; PG8_SCHED;
;             PG8_LDB(B1, 0, 1); PG8_STAGE(PG8_SB(0, 0), b2, voffB);
;             PG8_BAR; PG8_WAIT_L(0); PG8_MMA(0, 1, At, B1); PG8_BAR;
;             PG8_LDA(At, 0, 1); PG8_STAGE(PG8_SA(0, 0), a2, voffA);
;             PG8_BAR; PG8_WAIT_L(0); PG8_MMA(1, 0, At, B0); PG8_BAR; PG8_SCHED;
.LBB0_1273:
	ds_read_b128 v[144:147], v154
	ds_read_b128 v[158:161], v154 offset:1024
	ds_read_b128 v[162:165], v154 offset:2048
	ds_read_b128 v[166:169], v154 offset:3072
	s_add_u32 s20, s16, 0xfff50080
	s_addc_u32 s21, s17, -1
	s_cmp_eq_u32 s48, 40
	s_cselect_b32 s25, s5, s21
	s_cselect_b32 s24, s4, s20
	s_cselect_b32 s21, s7, s47
	s_cselect_b32 s20, s6, s46
	v_lshl_add_u64 v[174:175], s[16:17], 0, v[136:137]
	s_add_i32 m0, s29, 0xc000
	ds_read_b128 v[170:173], v155
	ds_read_b128 v[178:181], v155 offset:1024
	ds_read_b128 v[182:185], v155 offset:2048
	ds_read_b128 v[186:189], v155 offset:3072
	ds_read_b128 v[190:193], v155 offset:4096
	ds_read_b128 v[194:197], v155 offset:5120
	ds_read_b128 v[198:201], v155 offset:6144
	ds_read_b128 v[202:205], v155 offset:7168
	global_load_lds_dwordx4 v[174:175], off
	v_lshl_add_u64 v[174:175], s[16:17], 0, v[138:139]
	s_add_i32 m0, s29, 0xe000
	s_nop 0
	global_load_lds_dwordx4 v[174:175], off
	s_waitcnt lgkmcnt(8)
	s_barrier
	s_waitcnt lgkmcnt(0)
	s_setprio 1
	s_waitcnt lgkmcnt(0)
	v_mfma_f32_16x16x32_bf16 v[124:127], v[144:147], v[170:173], v[124:127]
	v_mfma_f32_16x16x32_bf16 v[120:123], v[162:165], v[170:173], v[120:123]
	v_mfma_f32_16x16x32_bf16 v[108:111], v[144:147], v[182:185], v[108:111]
	v_mfma_f32_16x16x32_bf16 v[104:107], v[162:165], v[182:185], v[104:107]
	v_mfma_f32_16x16x32_bf16 v[92:95], v[144:147], v[190:193], v[92:95]
	v_mfma_f32_16x16x32_bf16 v[88:91], v[162:165], v[190:193], v[88:91]
	v_mfma_f32_16x16x32_bf16 v[76:79], v[144:147], v[198:201], v[76:79]
	v_mfma_f32_16x16x32_bf16 v[72:75], v[162:165], v[198:201], v[72:75]
	v_mfma_f32_16x16x32_bf16 v[124:127], v[158:161], v[178:181], v[124:127]
	v_mfma_f32_16x16x32_bf16 v[120:123], v[166:169], v[178:181], v[120:123]
	v_mfma_f32_16x16x32_bf16 v[108:111], v[158:161], v[186:189], v[108:111]
	v_mfma_f32_16x16x32_bf16 v[104:107], v[166:169], v[186:189], v[104:107]
	v_mfma_f32_16x16x32_bf16 v[92:95], v[158:161], v[194:197], v[92:95]
	v_mfma_f32_16x16x32_bf16 v[88:91], v[166:169], v[194:197], v[88:91]
	v_mfma_f32_16x16x32_bf16 v[76:79], v[158:161], v[202:205], v[76:79]
	v_mfma_f32_16x16x32_bf16 v[72:75], v[166:169], v[202:205], v[72:75]
	s_setprio 0
	s_barrier
	s_add_i32 s49, s40, s28
	v_lshl_add_u64 v[174:175], s[20:21], 0, v[130:131]
	s_mov_b32 m0, s49
	ds_read_b128 v[206:209], v156
	ds_read_b128 v[210:213], v156 offset:1024
	ds_read_b128 v[214:217], v156 offset:2048
	ds_read_b128 v[218:221], v156 offset:3072
	global_load_lds_dwordx4 v[174:175], off
	v_lshl_add_u64 v[222:223], s[20:21], 0, v[134:135]
	s_add_i32 m0, s49, 0x2000
	s_nop 0
	global_load_lds_dwordx4 v[222:223], off
	s_barrier
	s_waitcnt lgkmcnt(0)
	s_setprio 1
	s_waitcnt lgkmcnt(0)
	v_mfma_f32_16x16x32_bf16 v[116:119], v[206:209], v[170:173], v[116:119]
	v_mfma_f32_16x16x32_bf16 v[112:115], v[214:217], v[170:173], v[112:115]
	v_mfma_f32_16x16x32_bf16 v[100:103], v[206:209], v[182:185], v[100:103]
	v_mfma_f32_16x16x32_bf16 v[96:99], v[214:217], v[182:185], v[96:99]
	v_mfma_f32_16x16x32_bf16 v[84:87], v[206:209], v[190:193], v[84:87]
	v_mfma_f32_16x16x32_bf16 v[80:83], v[214:217], v[190:193], v[80:83]
	v_mfma_f32_16x16x32_bf16 v[68:71], v[206:209], v[198:201], v[68:71]
	v_mfma_f32_16x16x32_bf16 v[64:67], v[214:217], v[198:201], v[64:67]
	v_mfma_f32_16x16x32_bf16 v[116:119], v[210:213], v[178:181], v[116:119]
	v_mfma_f32_16x16x32_bf16 v[112:115], v[218:221], v[178:181], v[112:115]
	v_mfma_f32_16x16x32_bf16 v[100:103], v[210:213], v[186:189], v[100:103]
	v_mfma_f32_16x16x32_bf16 v[96:99], v[218:221], v[186:189], v[96:99]
	v_mfma_f32_16x16x32_bf16 v[84:87], v[210:213], v[194:197], v[84:87]
	v_mfma_f32_16x16x32_bf16 v[80:83], v[218:221], v[194:197], v[80:83]
	v_mfma_f32_16x16x32_bf16 v[68:71], v[210:213], v[202:205], v[68:71]
	v_mfma_f32_16x16x32_bf16 v[64:67], v[218:221], v[202:205], v[64:67]
	s_setprio 0
	s_mov_b32 m0, s29
	v_lshl_add_u64 v[224:225], s[24:25], 0, v[128:129]
	s_barrier
	ds_read_b128 v[170:173], v155 offset:16384
	ds_read_b128 v[178:181], v155 offset:17408
	ds_read_b128 v[182:185], v155 offset:18432
	ds_read_b128 v[186:189], v155 offset:19456
	ds_read_b128 v[190:193], v155 offset:20480
	ds_read_b128 v[194:197], v155 offset:21504
	ds_read_b128 v[198:201], v155 offset:22528
	ds_read_b128 v[202:205], v155 offset:23552
	global_load_lds_dwordx4 v[224:225], off
	v_lshl_add_u64 v[226:227], s[24:25], 0, v[132:133]
	s_mov_b32 m0, s30
	s_nop 0
	global_load_lds_dwordx4 v[226:227], off
	s_barrier
	s_waitcnt lgkmcnt(0)
	s_setprio 1
	s_waitcnt lgkmcnt(0)
	v_mfma_f32_16x16x32_bf16 v[60:63], v[144:147], v[170:173], v[60:63]
	v_mfma_f32_16x16x32_bf16 v[56:59], v[162:165], v[170:173], v[56:59]
	v_mfma_f32_16x16x32_bf16 v[44:47], v[144:147], v[182:185], v[44:47]
	v_mfma_f32_16x16x32_bf16 v[40:43], v[162:165], v[182:185], v[40:43]
	v_mfma_f32_16x16x32_bf16 v[28:31], v[144:147], v[190:193], v[28:31]
	v_mfma_f32_16x16x32_bf16 v[24:27], v[162:165], v[190:193], v[24:27]
	v_mfma_f32_16x16x32_bf16 v[12:15], v[144:147], v[198:201], v[12:15]
	v_mfma_f32_16x16x32_bf16 v[8:11], v[162:165], v[198:201], v[8:11]
	v_mfma_f32_16x16x32_bf16 v[60:63], v[158:161], v[178:181], v[60:63]
	v_mfma_f32_16x16x32_bf16 v[56:59], v[166:169], v[178:181], v[56:59]
	v_mfma_f32_16x16x32_bf16 v[44:47], v[158:161], v[186:189], v[44:47]
	v_mfma_f32_16x16x32_bf16 v[40:43], v[166:169], v[186:189], v[40:43]
	v_mfma_f32_16x16x32_bf16 v[28:31], v[158:161], v[194:197], v[28:31]
	v_mfma_f32_16x16x32_bf16 v[24:27], v[166:169], v[194:197], v[24:27]
	v_mfma_f32_16x16x32_bf16 v[12:15], v[158:161], v[202:205], v[12:15]
	v_mfma_f32_16x16x32_bf16 v[8:11], v[166:169], v[202:205], v[8:11]
	s_setprio 0
	s_barrier
; #define PG8_STAGE(bufoff, gbase, voff) do { _Pragma("unroll") for (int _i = 0; _i < 2; ++_i) \
;         __builtin_amdgcn_global_load_lds((const unsigned*)((const char*)(gbase) + (voff)[_i]), (LAS unsigned*)(lds + (bufoff) + ldsw + _i * 8192), 16, 0, 0); } while (0)
; #define PG8_LDA(dst, b, h) do { _Pragma("unroll") for (int m = 0; m < 4; ++m) _Pragma("unroll") for (int k = 0; k < 2; ++k) dst[m][k] = *(const LAS bf16x8*)(lds + PG8_SA(b, h) + aoff + m * 2048 + k * 1024); } while (0)
; #define PG8_LDB(dst, b, h) do { _Pragma("unroll") for (int n = 0; n < 2; ++n) _Pragma("unroll") for (int k = 0; k < 2; ++k) dst[n][k] = *(const LAS bf16x8*)(lds + PG8_SB(b, h) + boff + n * 2048 + k * 1024); } while (0)
; #define PG8_MMA(ai, bj, At, Bt) do { __builtin_amdgcn_s_setprio(1); _Pragma("unroll") for (int m = 0; m < 4; ++m) _Pragma("unroll") for (int n = 0; n < 2; ++n) _Pragma("unroll") for (int k = 0; k < 2; ++k) \
;         acc[ai][bj][m][n] = __builtin_amdgcn_mfma_f32_16x16x32_bf16(Bt[n][k], At[m][k], acc[ai][bj][m][n], 0, 0, 0); __builtin_amdgcn_s_setprio(0); } while (0)
; #define PG8_WAIT_V(n) asm volatile("s_waitcnt vmcnt(" #n ")" ::: "memory")
; #define PG8_WAIT_L(n) asm volatile("s_waitcnt lgkmcnt(" #n ")" ::: "memory")
; #define PG8_BAR __builtin_amdgcn_s_barrier()
; #define PG8_SCHED __builtin_amdgcn_sched_barrier(0)
; template <class Epi>
; __device__ __forceinline__ void gemm_phase(LAS unsigned char* lds, const Gemm g, const StaticOrder& S, const Epi& E) {
;     ...
;             PG8_STAGE(PG8_SB(0, 1), b2 + hstepB, voffB);
;             PG8_WAIT_V(6); PG8_BAR; PG8_MMA(1, 1, At, B1); PG8_BAR;
;             PG8_LDB(B0, 1, 0); PG8_SCHED; PG8_LDA(At, 1, 0); PG8_STAGE(PG8_SA(0, 1), a2 + hstepA, voffA);
;             PG8_WAIT_L(8); PG8_BAR; PG8_WAIT_L(0); PG8_MMA(0, 0, At, B0); PG8_BAR; PG8_SCHED;
;             PG8_LDB(B1, 1, 1); PG8_STAGE(PG8_SB(1, 0), b3, voffB);
;             PG8_BAR; PG8_WAIT_L(0); PG8_MMA(0, 1, At, B1); PG8_BAR;
;             PG8_LDA(At, 1, 1); PG8_STAGE(PG8_SA(1, 0), a3, voffA);
	s_add_u32 s50, s20, 0xb0000
	s_addc_u32 s51, s21, 0
	s_add_i32 s49, s41, s28
	v_lshl_add_u64 v[144:145], s[50:51], 0, v[130:131]
	s_mov_b32 m0, s49
	s_nop 0
	global_load_lds_dwordx4 v[144:145], off
	v_lshl_add_u64 v[144:145], s[50:51], 0, v[134:135]
	s_add_i32 m0, s49, 0x2000
	s_nop 0
	global_load_lds_dwordx4 v[144:145], off
	s_waitcnt vmcnt(6)
	s_barrier
	s_setprio 1
	v_mfma_f32_16x16x32_bf16 v[52:55], v[206:209], v[170:173], v[52:55]
	v_mfma_f32_16x16x32_bf16 v[48:51], v[214:217], v[170:173], v[48:51]
	v_mfma_f32_16x16x32_bf16 v[36:39], v[206:209], v[182:185], v[36:39]
	v_mfma_f32_16x16x32_bf16 v[32:35], v[214:217], v[182:185], v[32:35]
	v_mfma_f32_16x16x32_bf16 v[20:23], v[206:209], v[190:193], v[20:23]
	v_mfma_f32_16x16x32_bf16 v[16:19], v[214:217], v[190:193], v[16:19]
	v_mfma_f32_16x16x32_bf16 v[4:7], v[206:209], v[198:201], v[4:7]
	v_mfma_f32_16x16x32_bf16 v[0:3], v[214:217], v[198:201], v[0:3]
	v_mfma_f32_16x16x32_bf16 v[52:55], v[210:213], v[178:181], v[52:55]
	v_mfma_f32_16x16x32_bf16 v[48:51], v[218:221], v[178:181], v[48:51]
	v_mfma_f32_16x16x32_bf16 v[36:39], v[210:213], v[186:189], v[36:39]
	v_mfma_f32_16x16x32_bf16 v[32:35], v[218:221], v[186:189], v[32:35]
	v_mfma_f32_16x16x32_bf16 v[20:23], v[210:213], v[194:197], v[20:23]
	v_mfma_f32_16x16x32_bf16 v[16:19], v[218:221], v[194:197], v[16:19]
	v_mfma_f32_16x16x32_bf16 v[4:7], v[210:213], v[202:205], v[4:7]
	v_mfma_f32_16x16x32_bf16 v[0:3], v[218:221], v[202:205], v[0:3]
	s_setprio 0
	s_add_i32 s49, 0, 0x18000
	v_add_u32_e32 v166, s49, v152
	s_barrier
	ds_read_b128 v[144:147], v166
	ds_read_b128 v[158:161], v166 offset:1024
	ds_read_b128 v[162:165], v166 offset:2048
	ds_read_b128 v[166:169], v166 offset:3072
	s_add_u32 s24, s24, 0xb0000
	s_addc_u32 s25, s25, 0
	s_mov_b32 m0, s31
	v_lshl_add_u64 v[206:207], s[24:25], 0, v[128:129]
	ds_read_b128 v[170:173], v155 offset:32768
	ds_read_b128 v[178:181], v155 offset:33792
	ds_read_b128 v[182:185], v155 offset:34816
	ds_read_b128 v[186:189], v155 offset:35840
	ds_read_b128 v[190:193], v155 offset:36864
	ds_read_b128 v[194:197], v155 offset:37888
	ds_read_b128 v[198:201], v155 offset:38912
	ds_read_b128 v[202:205], v155 offset:39936
	global_load_lds_dwordx4 v[206:207], off
	v_lshl_add_u64 v[206:207], s[24:25], 0, v[132:133]
	s_mov_b32 m0, s33
	s_nop 0
	global_load_lds_dwordx4 v[206:207], off
	s_waitcnt lgkmcnt(8)
	s_barrier
	s_waitcnt lgkmcnt(0)
	s_setprio 1
	s_waitcnt lgkmcnt(0)
	v_mfma_f32_16x16x32_bf16 v[124:127], v[144:147], v[170:173], v[124:127]
	v_mfma_f32_16x16x32_bf16 v[120:123], v[162:165], v[170:173], v[120:123]
	v_mfma_f32_16x16x32_bf16 v[108:111], v[144:147], v[182:185], v[108:111]
	v_mfma_f32_16x16x32_bf16 v[104:107], v[162:165], v[182:185], v[104:107]
	v_mfma_f32_16x16x32_bf16 v[92:95], v[144:147], v[190:193], v[92:95]
	v_mfma_f32_16x16x32_bf16 v[88:91], v[162:165], v[190:193], v[88:91]
	v_mfma_f32_16x16x32_bf16 v[76:79], v[144:147], v[198:201], v[76:79]
	v_mfma_f32_16x16x32_bf16 v[72:75], v[162:165], v[198:201], v[72:75]
	v_mfma_f32_16x16x32_bf16 v[124:127], v[158:161], v[178:181], v[124:127]
	v_mfma_f32_16x16x32_bf16 v[120:123], v[166:169], v[178:181], v[120:123]
	v_mfma_f32_16x16x32_bf16 v[108:111], v[158:161], v[186:189], v[108:111]
	v_mfma_f32_16x16x32_bf16 v[104:107], v[166:169], v[186:189], v[104:107]
	v_mfma_f32_16x16x32_bf16 v[92:95], v[158:161], v[194:197], v[92:95]
	v_mfma_f32_16x16x32_bf16 v[88:91], v[166:169], v[194:197], v[88:91]
	v_mfma_f32_16x16x32_bf16 v[76:79], v[158:161], v[202:205], v[76:79]
	v_mfma_f32_16x16x32_bf16 v[72:75], v[166:169], v[202:205], v[72:75]
	s_setprio 0
	s_barrier
	s_add_i32 s24, 0, 0x1c000
	s_add_i32 s25, s49, s28
	v_add_u32_e32 v218, s24, v152
	v_lshl_add_u64 v[174:175], v[174:175], 0, s[14:15]
	s_mov_b32 m0, s25
	ds_read_b128 v[206:209], v218
	ds_read_b128 v[210:213], v218 offset:1024
	ds_read_b128 v[214:217], v218 offset:2048
	ds_read_b128 v[218:221], v218 offset:3072
	global_load_lds_dwordx4 v[174:175], off
	v_lshl_add_u64 v[174:175], v[222:223], 0, s[14:15]
	s_add_i32 m0, s25, 0x2000
	s_nop 0
	global_load_lds_dwordx4 v[174:175], off
	s_barrier
	s_waitcnt lgkmcnt(0)
	s_setprio 1
	s_waitcnt lgkmcnt(0)
	v_mfma_f32_16x16x32_bf16 v[116:119], v[206:209], v[170:173], v[116:119]
	v_mfma_f32_16x16x32_bf16 v[112:115], v[214:217], v[170:173], v[112:115]
	v_mfma_f32_16x16x32_bf16 v[100:103], v[206:209], v[182:185], v[100:103]
	v_mfma_f32_16x16x32_bf16 v[96:99], v[214:217], v[182:185], v[96:99]
	v_mfma_f32_16x16x32_bf16 v[84:87], v[206:209], v[190:193], v[84:87]
	v_mfma_f32_16x16x32_bf16 v[80:83], v[214:217], v[190:193], v[80:83]
	v_mfma_f32_16x16x32_bf16 v[68:71], v[206:209], v[198:201], v[68:71]
	v_mfma_f32_16x16x32_bf16 v[64:67], v[214:217], v[198:201], v[64:67]
	v_mfma_f32_16x16x32_bf16 v[116:119], v[210:213], v[178:181], v[116:119]
	v_mfma_f32_16x16x32_bf16 v[112:115], v[218:221], v[178:181], v[112:115]
	v_mfma_f32_16x16x32_bf16 v[100:103], v[210:213], v[186:189], v[100:103]
	v_mfma_f32_16x16x32_bf16 v[96:99], v[218:221], v[186:189], v[96:99]
	v_mfma_f32_16x16x32_bf16 v[84:87], v[210:213], v[194:197], v[84:87]
	v_mfma_f32_16x16x32_bf16 v[80:83], v[218:221], v[194:197], v[80:83]
	v_mfma_f32_16x16x32_bf16 v[68:71], v[210:213], v[202:205], v[68:71]
	v_mfma_f32_16x16x32_bf16 v[64:67], v[218:221], v[202:205], v[64:67]
	s_setprio 0
	s_mov_b32 m0, s35
	v_lshl_add_u64 v[174:175], v[224:225], 0, s[14:15]
	s_barrier
	ds_read_b128 v[170:173], v155 offset:49152
	ds_read_b128 v[178:181], v155 offset:50176
	ds_read_b128 v[182:185], v155 offset:51200
	ds_read_b128 v[186:189], v155 offset:52224
	ds_read_b128 v[190:193], v155 offset:53248
	ds_read_b128 v[194:197], v155 offset:54272
	ds_read_b128 v[198:201], v155 offset:55296
	ds_read_b128 v[202:205], v155 offset:56320
	global_load_lds_dwordx4 v[174:175], off
	v_lshl_add_u64 v[174:175], v[226:227], 0, s[14:15]
	s_mov_b32 m0, s36
	s_nop 0
	global_load_lds_dwordx4 v[174:175], off
	s_barrier
; __device__ __forceinline__ unsigned pk2(float lo, float hi) { f32x2 v; v.x = lo; v.y = hi; return __builtin_bit_cast(unsigned, __builtin_convertvector(v, hwbf2)); }
; #define PG8_STAGE(bufoff, gbase, voff) do { _Pragma("unroll") for (int _i = 0; _i < 2; ++_i) \
;         __builtin_amdgcn_global_load_lds((const unsigned*)((const char*)(gbase) + (voff)[_i]), (LAS unsigned*)(lds + (bufoff) + ldsw + _i * 8192), 16, 0, 0); } while (0)
; #define PG8_MMA(ai, bj, At, Bt) do { __builtin_amdgcn_s_setprio(1); _Pragma("unroll") for (int m = 0; m < 4; ++m) _Pragma("unroll") for (int n = 0; n < 2; ++n) _Pragma("unroll") for (int k = 0; k < 2; ++k) \
;         acc[ai][bj][m][n] = __builtin_amdgcn_mfma_f32_16x16x32_bf16(Bt[n][k], At[m][k], acc[ai][bj][m][n], 0, 0, 0); __builtin_amdgcn_s_setprio(0); } while (0)
; #define PG8_WAIT_V(n) asm volatile("s_waitcnt vmcnt(" #n ")" ::: "memory")
; #define PG8_WAIT_L(n) asm volatile("s_waitcnt lgkmcnt(" #n ")" ::: "memory")
; #define PG8_BAR __builtin_amdgcn_s_barrier()
; #define PG8_SCHED __builtin_amdgcn_sched_barrier(0)
; template <class Epi>
; __device__ __forceinline__ void gemm_phase(LAS unsigned char* lds, const Gemm g, const StaticOrder& S, const Epi& E) {
;     ...
;             PG8_BAR; PG8_WAIT_L(0); PG8_MMA(1, 0, At, B0); PG8_BAR; PG8_SCHED;
;             PG8_STAGE(PG8_SB(1, 1), b3 + hstepB, voffB);
;             PG8_WAIT_V(6); PG8_BAR; PG8_MMA(1, 1, At, B1); PG8_BAR;
;         }
;     __device__ __forceinline__ void operator()(const f32x4 (&acc)[2][2][4][2], const pg8::Unit& u, int wr, int wc, int fr, int fq) const {
;     ...
;             for (int m = 0; m < 4; ++m) { const int row = row0 + ai * 128 + m * 16; bf16_t* rowp = O + (size_t)row * ldc + col0; float ss = 0.f;
; #pragma unroll
;                 for (int bj = 0; bj < 2; ++bj) { const f32x4 v0 = acc[ai][bj][m][0], v1 = acc[ai][bj][m][1];
;                     ss += (v0[0] * v0[0] + v0[1] * v0[1]) + (v0[2] * v0[2] + v0[3] * v0[3]) + (v1[0] * v1[0] + v1[1] * v1[1]) + (v1[2] * v1[2] + v1[3] * v1[3]);
;                     u32x4 w; w.x = pk2(v0[0], v0[1]); w.y = pk2(v0[2], v0[3]); w.z = pk2(v1[0], v1[1]); w.w = pk2(v1[2], v1[3]);
;                     *(u32x4*)(rowp + bj * 128) = w; }
;                 ss += __shfl_xor(ss, 16); ss += __shfl_xor(ss, 32);
;                 if (fq == 0) atomicAdd(sumsq + row, ss); }
	s_waitcnt lgkmcnt(0)
	s_setprio 1
	s_waitcnt lgkmcnt(0)
	v_mfma_f32_16x16x32_bf16 v[60:63], v[144:147], v[170:173], v[60:63]
	v_mfma_f32_16x16x32_bf16 v[56:59], v[162:165], v[170:173], v[56:59]
	v_mfma_f32_16x16x32_bf16 v[44:47], v[144:147], v[182:185], v[44:47]
	v_mfma_f32_16x16x32_bf16 v[40:43], v[162:165], v[182:185], v[40:43]
	v_mfma_f32_16x16x32_bf16 v[28:31], v[144:147], v[190:193], v[28:31]
	v_mfma_f32_16x16x32_bf16 v[24:27], v[162:165], v[190:193], v[24:27]
	v_mfma_f32_16x16x32_bf16 v[12:15], v[144:147], v[198:201], v[12:15]
	v_mfma_f32_16x16x32_bf16 v[8:11], v[162:165], v[198:201], v[8:11]
	v_mfma_f32_16x16x32_bf16 v[60:63], v[158:161], v[178:181], v[60:63]
	v_mfma_f32_16x16x32_bf16 v[56:59], v[166:169], v[178:181], v[56:59]
	v_mfma_f32_16x16x32_bf16 v[44:47], v[158:161], v[186:189], v[44:47]
	v_mfma_f32_16x16x32_bf16 v[40:43], v[166:169], v[186:189], v[40:43]
	v_mfma_f32_16x16x32_bf16 v[28:31], v[158:161], v[194:197], v[28:31]
	v_mfma_f32_16x16x32_bf16 v[24:27], v[166:169], v[194:197], v[24:27]
	v_mfma_f32_16x16x32_bf16 v[12:15], v[158:161], v[202:205], v[12:15]
	v_mfma_f32_16x16x32_bf16 v[8:11], v[166:169], v[202:205], v[8:11]
	s_setprio 0
	s_barrier
	s_add_u32 s20, s20, 0xb0080
	s_addc_u32 s21, s21, 0
	s_add_i32 s24, s24, s28
	v_lshl_add_u64 v[144:145], s[20:21], 0, v[130:131]
	s_mov_b32 m0, s24
	s_nop 0
	global_load_lds_dwordx4 v[144:145], off
	v_lshl_add_u64 v[144:145], s[20:21], 0, v[134:135]
	s_add_i32 m0, s24, 0x2000
	s_nop 0
	global_load_lds_dwordx4 v[144:145], off
	s_waitcnt vmcnt(6)
	s_barrier
	s_setprio 1
	v_mfma_f32_16x16x32_bf16 v[52:55], v[206:209], v[170:173], v[52:55]
	v_mfma_f32_16x16x32_bf16 v[48:51], v[214:217], v[170:173], v[48:51]
	v_mfma_f32_16x16x32_bf16 v[36:39], v[206:209], v[182:185], v[36:39]
	v_mfma_f32_16x16x32_bf16 v[32:35], v[214:217], v[182:185], v[32:35]
	v_mfma_f32_16x16x32_bf16 v[20:23], v[206:209], v[190:193], v[20:23]
	v_mfma_f32_16x16x32_bf16 v[16:19], v[214:217], v[190:193], v[16:19]
	v_mfma_f32_16x16x32_bf16 v[4:7], v[206:209], v[198:201], v[4:7]
	v_mfma_f32_16x16x32_bf16 v[0:3], v[214:217], v[198:201], v[0:3]
	v_mfma_f32_16x16x32_bf16 v[52:55], v[210:213], v[178:181], v[52:55]
	v_mfma_f32_16x16x32_bf16 v[48:51], v[218:221], v[178:181], v[48:51]
	v_mfma_f32_16x16x32_bf16 v[36:39], v[210:213], v[186:189], v[36:39]
	v_mfma_f32_16x16x32_bf16 v[32:35], v[218:221], v[186:189], v[32:35]
	v_mfma_f32_16x16x32_bf16 v[20:23], v[210:213], v[194:197], v[20:23]
	v_mfma_f32_16x16x32_bf16 v[16:19], v[218:221], v[194:197], v[16:19]
	v_mfma_f32_16x16x32_bf16 v[4:7], v[210:213], v[202:205], v[4:7]
	v_mfma_f32_16x16x32_bf16 v[0:3], v[218:221], v[202:205], v[0:3]
	s_setprio 0
	s_add_i32 s48, s48, 2
	s_add_u32 s16, s16, 0x100
	s_addc_u32 s17, s17, 0
	s_add_u32 s46, s46, 0x100
	s_addc_u32 s47, s47, 0
	s_cmp_gt_u32 s48, 41
	s_barrier
	s_cbranch_scc0 .LBB0_1273
	v_mul_f32_e32 v162, v125, v125
	v_mul_f32_e32 v163, v127, v127
	v_fmac_f32_e32 v162, v124, v124
	v_fmac_f32_e32 v163, v126, v126
	v_cvt_pk_bf16_f32 v124, v124, v125
	v_cvt_pk_bf16_f32 v125, v126, v127
	v_mul_f32_e32 v126, v117, v117
	v_mul_f32_e32 v127, v119, v119
	v_fmac_f32_e32 v126, v116, v116
	v_fmac_f32_e32 v127, v118, v118
	v_add_f32_e32 v162, v162, v163
	v_mul_f32_e32 v163, v121, v121
	v_add_f32_e32 v126, v126, v127
	v_mul_f32_e32 v127, v113, v113
	v_and_b32_e32 v158, 64, v157
	v_fmac_f32_e32 v163, v120, v120
	v_fmac_f32_e32 v127, v112, v112
	v_xor_b32_e32 v147, 16, v157
	v_add_u32_e32 v158, 64, v158
	v_add_f32_e32 v162, v162, v163
	v_mul_f32_e32 v163, v123, v123
	v_add_f32_e32 v126, v126, v127
	v_mul_f32_e32 v127, v115, v115
	v_cmp_lt_i32_e32 vcc, v147, v158
	v_fmac_f32_e32 v163, v122, v122
	v_fmac_f32_e32 v127, v114, v114
	v_cndmask_b32_e32 v147, v157, v147, vcc
	v_add_f32_e32 v162, v163, v162
	v_add_f32_e32 v126, v127, v126
	v_lshlrev_b32_e32 v159, 2, v147
	v_add_f32_e32 v162, v162, v126
	v_mov_b32_e32 v163, v162
	s_nop 1
	v_permlane16_swap_b32_e32 v162, v163
	v_xor_b32_e32 v147, 32, v157
	v_cmp_lt_i32_e32 vcc, v147, v158
	v_cvt_pk_bf16_f32 v126, v120, v121
	v_cvt_pk_bf16_f32 v120, v116, v117
	v_cndmask_b32_e32 v147, v157, v147, vcc
	v_lshlrev_b32_e32 v158, 2, v147
	s_waitcnt lgkmcnt(0)
	v_add_f32_e32 v116, v162, v163
	v_lshl_add_u32 v146, s45, 8, v151
	v_mov_b32_e32 v117, v116
	s_nop 1
	v_permlane32_swap_b32_e32 v116, v117
	v_ashrrev_i32_e32 v147, 31, v146
	v_lshl_or_b32 v144, s44, 8, v153
	v_lshlrev_b64 v[160:161], 11, v[146:147]
	v_ashrrev_i32_e32 v145, 31, v144
	v_lshl_add_u64 v[160:161], s[10:11], 0, v[160:161]
	v_lshl_add_u64 v[160:161], v[144:145], 1, v[160:161]
	v_cvt_pk_bf16_f32 v127, v122, v123
	v_cvt_pk_bf16_f32 v121, v118, v119
	v_cvt_pk_bf16_f32 v122, v112, v113
	v_cvt_pk_bf16_f32 v123, v114, v115
	global_store_dwordx4 v[160:161], v[124:127], off
	global_store_dwordx4 v[160:161], v[120:123], off offset:256
	s_and_saveexec_b64 s[16:17], s[0:1]
	s_cbranch_execz .LBB0_1276
	v_lshl_add_u64 v[112:113], v[146:147], 2, s[12:13]
	s_waitcnt lgkmcnt(0)
	v_add_f32_e32 v114, v116, v117
	global_atomic_add_f32 v[112:113], v114, off
; __device__ __forceinline__ unsigned pk2(float lo, float hi) { f32x2 v; v.x = lo; v.y = hi; return __builtin_bit_cast(unsigned, __builtin_convertvector(v, hwbf2)); }
;     __device__ __forceinline__ void operator()(const f32x4 (&acc)[2][2][4][2], const pg8::Unit& u, int wr, int wc, int fr, int fq) const {
;     ...
;             for (int m = 0; m < 4; ++m) { const int row = row0 + ai * 128 + m * 16; bf16_t* rowp = O + (size_t)row * ldc + col0; float ss = 0.f;
; #pragma unroll
;                 for (int bj = 0; bj < 2; ++bj) { const f32x4 v0 = acc[ai][bj][m][0], v1 = acc[ai][bj][m][1];
;                     ss += (v0[0] * v0[0] + v0[1] * v0[1]) + (v0[2] * v0[2] + v0[3] * v0[3]) + (v1[0] * v1[0] + v1[1] * v1[1]) + (v1[2] * v1[2] + v1[3] * v1[3]);
;                     u32x4 w; w.x = pk2(v0[0], v0[1]); w.y = pk2(v0[2], v0[3]); w.z = pk2(v1[0], v1[1]); w.w = pk2(v1[2], v1[3]);
;                     *(u32x4*)(rowp + bj * 128) = w; }
;                 ss += __shfl_xor(ss, 16); ss += __shfl_xor(ss, 32);
;                 if (fq == 0) atomicAdd(sumsq + row, ss); }
.LBB0_1276:
	s_or_b64 exec, exec, s[16:17]
	v_mul_f32_e32 v116, v109, v109
	s_waitcnt lgkmcnt(0)
	v_mul_f32_e32 v117, v111, v111
	v_fmac_f32_e32 v116, v108, v108
	v_fmac_f32_e32 v117, v110, v110
	v_cvt_pk_bf16_f32 v108, v108, v109
	v_cvt_pk_bf16_f32 v109, v110, v111
	v_mul_f32_e32 v110, v101, v101
	v_mul_f32_e32 v111, v103, v103
	v_fmac_f32_e32 v110, v100, v100
	v_fmac_f32_e32 v111, v102, v102
	v_add_f32_e32 v116, v116, v117
	v_mul_f32_e32 v117, v105, v105
	v_add_f32_e32 v110, v110, v111
	v_mul_f32_e32 v111, v97, v97
	v_fmac_f32_e32 v117, v104, v104
	v_fmac_f32_e32 v111, v96, v96
	v_add_f32_e32 v116, v116, v117
	v_mul_f32_e32 v117, v107, v107
	v_add_f32_e32 v110, v110, v111
	v_mul_f32_e32 v111, v99, v99
	v_fmac_f32_e32 v117, v106, v106
	v_fmac_f32_e32 v111, v98, v98
	v_add_f32_e32 v116, v117, v116
	v_add_f32_e32 v110, v111, v110
	v_add_f32_e32 v116, v116, v110
	v_mov_b32_e32 v117, v116
	s_nop 1
	v_permlane16_swap_b32_e32 v116, v117
	v_cvt_pk_bf16_f32 v110, v104, v105
	v_cvt_pk_bf16_f32 v104, v100, v101
	v_or_b32_e32 v112, 16, v146
	v_ashrrev_i32_e32 v113, 31, v112
	s_waitcnt lgkmcnt(0)
	v_add_f32_e32 v100, v116, v117
	v_mov_b32_e32 v101, v100
	s_nop 1
	v_permlane32_swap_b32_e32 v100, v101
	v_lshlrev_b64 v[114:115], 11, v[112:113]
	v_lshl_add_u64 v[114:115], s[10:11], 0, v[114:115]
	v_lshl_add_u64 v[114:115], v[144:145], 1, v[114:115]
	v_cvt_pk_bf16_f32 v111, v106, v107
	v_cvt_pk_bf16_f32 v105, v102, v103
	v_cvt_pk_bf16_f32 v106, v96, v97
	v_cvt_pk_bf16_f32 v107, v98, v99
	global_store_dwordx4 v[114:115], v[108:111], off
	global_store_dwordx4 v[114:115], v[104:107], off offset:256
	s_and_saveexec_b64 s[16:17], s[0:1]
	s_cbranch_execz .LBB0_1278
	v_lshl_add_u64 v[96:97], v[112:113], 2, s[12:13]
	s_waitcnt lgkmcnt(0)
	v_add_f32_e32 v98, v100, v101
	global_atomic_add_f32 v[96:97], v98, off
.LBB0_1278:
	s_or_b64 exec, exec, s[16:17]
	v_mul_f32_e32 v100, v93, v93
	s_waitcnt lgkmcnt(0)
	v_mul_f32_e32 v101, v95, v95
	v_fmac_f32_e32 v100, v92, v92
	v_fmac_f32_e32 v101, v94, v94
	v_cvt_pk_bf16_f32 v92, v92, v93
	v_cvt_pk_bf16_f32 v93, v94, v95
	v_mul_f32_e32 v94, v85, v85
	v_mul_f32_e32 v95, v87, v87
	v_fmac_f32_e32 v94, v84, v84
	v_fmac_f32_e32 v95, v86, v86
	v_add_f32_e32 v100, v100, v101
	v_mul_f32_e32 v101, v89, v89
	v_add_f32_e32 v94, v94, v95
	v_mul_f32_e32 v95, v81, v81
	v_fmac_f32_e32 v101, v88, v88
	v_fmac_f32_e32 v95, v80, v80
	v_add_f32_e32 v100, v100, v101
	v_mul_f32_e32 v101, v91, v91
	v_add_f32_e32 v94, v94, v95
	v_mul_f32_e32 v95, v83, v83
	v_fmac_f32_e32 v101, v90, v90
	v_fmac_f32_e32 v95, v82, v82
	v_add_f32_e32 v100, v101, v100
	v_add_f32_e32 v94, v95, v94
	v_add_f32_e32 v100, v100, v94
	v_mov_b32_e32 v101, v100
	s_nop 1
	v_permlane16_swap_b32_e32 v100, v101
	v_cvt_pk_bf16_f32 v94, v88, v89
	v_cvt_pk_bf16_f32 v88, v84, v85
	v_or_b32_e32 v96, 32, v146
	v_ashrrev_i32_e32 v97, 31, v96
	s_waitcnt lgkmcnt(0)
	v_add_f32_e32 v84, v100, v101
	v_mov_b32_e32 v85, v84
	s_nop 1
	v_permlane32_swap_b32_e32 v84, v85
	v_lshlrev_b64 v[98:99], 11, v[96:97]
	v_lshl_add_u64 v[98:99], s[10:11], 0, v[98:99]
	v_lshl_add_u64 v[98:99], v[144:145], 1, v[98:99]
	v_cvt_pk_bf16_f32 v95, v90, v91
	v_cvt_pk_bf16_f32 v89, v86, v87
	v_cvt_pk_bf16_f32 v90, v80, v81
	v_cvt_pk_bf16_f32 v91, v82, v83
	global_store_dwordx4 v[98:99], v[92:95], off
	global_store_dwordx4 v[98:99], v[88:91], off offset:256
	s_and_saveexec_b64 s[16:17], s[0:1]
	s_cbranch_execz .LBB0_1280
	v_lshl_add_u64 v[80:81], v[96:97], 2, s[12:13]
	s_waitcnt lgkmcnt(0)
	v_add_f32_e32 v82, v84, v85
	global_atomic_add_f32 v[80:81], v82, off
.LBB0_1280:
	s_or_b64 exec, exec, s[16:17]
	v_mul_f32_e32 v84, v77, v77
	s_waitcnt lgkmcnt(0)
	v_mul_f32_e32 v85, v79, v79
	v_fmac_f32_e32 v84, v76, v76
	v_fmac_f32_e32 v85, v78, v78
	v_cvt_pk_bf16_f32 v76, v76, v77
	v_cvt_pk_bf16_f32 v77, v78, v79
	v_mul_f32_e32 v78, v69, v69
	v_mul_f32_e32 v79, v71, v71
	v_fmac_f32_e32 v78, v68, v68
	v_fmac_f32_e32 v79, v70, v70
	v_add_f32_e32 v84, v84, v85
	v_mul_f32_e32 v85, v73, v73
	v_add_f32_e32 v78, v78, v79
	v_mul_f32_e32 v79, v65, v65
	v_fmac_f32_e32 v85, v72, v72
	v_fmac_f32_e32 v79, v64, v64
	v_add_f32_e32 v84, v84, v85
	v_mul_f32_e32 v85, v75, v75
	v_add_f32_e32 v78, v78, v79
	v_mul_f32_e32 v79, v67, v67
	v_fmac_f32_e32 v85, v74, v74
	v_fmac_f32_e32 v79, v66, v66
	v_add_f32_e32 v84, v85, v84
	v_add_f32_e32 v78, v79, v78
	v_add_f32_e32 v84, v84, v78
	v_mov_b32_e32 v85, v84
	s_nop 1
	v_permlane16_swap_b32_e32 v84, v85
	v_cvt_pk_bf16_f32 v78, v72, v73
	v_cvt_pk_bf16_f32 v72, v68, v69
	v_or_b32_e32 v80, 48, v146
	v_ashrrev_i32_e32 v81, 31, v80
	s_waitcnt lgkmcnt(0)
	v_add_f32_e32 v68, v84, v85
	v_mov_b32_e32 v69, v68
	s_nop 1
	v_permlane32_swap_b32_e32 v68, v69
	v_lshlrev_b64 v[82:83], 11, v[80:81]
	v_lshl_add_u64 v[82:83], s[10:11], 0, v[82:83]
	v_lshl_add_u64 v[82:83], v[144:145], 1, v[82:83]
	v_cvt_pk_bf16_f32 v79, v74, v75
	v_cvt_pk_bf16_f32 v73, v70, v71
	v_cvt_pk_bf16_f32 v74, v64, v65
	v_cvt_pk_bf16_f32 v75, v66, v67
	global_store_dwordx4 v[82:83], v[76:79], off
	global_store_dwordx4 v[82:83], v[72:75], off offset:256
	s_and_saveexec_b64 s[16:17], s[0:1]
	s_cbranch_execz .LBB0_1282
	v_lshl_add_u64 v[64:65], v[80:81], 2, s[12:13]
	s_waitcnt lgkmcnt(0)
	v_add_f32_e32 v66, v68, v69
	global_atomic_add_f32 v[64:65], v66, off
; __device__ __forceinline__ unsigned pk2(float lo, float hi) { f32x2 v; v.x = lo; v.y = hi; return __builtin_bit_cast(unsigned, __builtin_convertvector(v, hwbf2)); }
;     __device__ __forceinline__ void operator()(const f32x4 (&acc)[2][2][4][2], const pg8::Unit& u, int wr, int wc, int fr, int fq) const {
;     ...
;             for (int m = 0; m < 4; ++m) { const int row = row0 + ai * 128 + m * 16; bf16_t* rowp = O + (size_t)row * ldc + col0; float ss = 0.f;
; #pragma unroll
;                 for (int bj = 0; bj < 2; ++bj) { const f32x4 v0 = acc[ai][bj][m][0], v1 = acc[ai][bj][m][1];
;                     ss += (v0[0] * v0[0] + v0[1] * v0[1]) + (v0[2] * v0[2] + v0[3] * v0[3]) + (v1[0] * v1[0] + v1[1] * v1[1]) + (v1[2] * v1[2] + v1[3] * v1[3]);
;                     u32x4 w; w.x = pk2(v0[0], v0[1]); w.y = pk2(v0[2], v0[3]); w.z = pk2(v1[0], v1[1]); w.w = pk2(v1[2], v1[3]);
;                     *(u32x4*)(rowp + bj * 128) = w; }
;                 ss += __shfl_xor(ss, 16); ss += __shfl_xor(ss, 32);
;                 if (fq == 0) atomicAdd(sumsq + row, ss); }
.LBB0_1282:
	s_or_b64 exec, exec, s[16:17]
	v_mul_f32_e32 v68, v61, v61
	s_waitcnt lgkmcnt(0)
	v_mul_f32_e32 v69, v63, v63
	v_fmac_f32_e32 v68, v60, v60
	v_fmac_f32_e32 v69, v62, v62
	v_cvt_pk_bf16_f32 v60, v60, v61
	v_cvt_pk_bf16_f32 v61, v62, v63
	v_mul_f32_e32 v62, v53, v53
	v_mul_f32_e32 v63, v55, v55
	v_fmac_f32_e32 v62, v52, v52
	v_fmac_f32_e32 v63, v54, v54
	v_add_f32_e32 v68, v68, v69
	v_mul_f32_e32 v69, v57, v57
	v_add_f32_e32 v62, v62, v63
	v_mul_f32_e32 v63, v49, v49
	v_fmac_f32_e32 v69, v56, v56
	v_fmac_f32_e32 v63, v48, v48
	v_add_f32_e32 v68, v68, v69
	v_mul_f32_e32 v69, v59, v59
	v_add_f32_e32 v62, v62, v63
	v_mul_f32_e32 v63, v51, v51
	v_fmac_f32_e32 v69, v58, v58
	v_fmac_f32_e32 v63, v50, v50
	v_add_f32_e32 v68, v69, v68
	v_add_f32_e32 v62, v63, v62
	v_add_f32_e32 v68, v68, v62
	v_mov_b32_e32 v69, v68
	s_nop 1
	v_permlane16_swap_b32_e32 v68, v69
	v_cvt_pk_bf16_f32 v62, v56, v57
	v_cvt_pk_bf16_f32 v56, v52, v53
	v_add_u32_e32 v64, 0x80, v146
	v_ashrrev_i32_e32 v65, 31, v64
	s_waitcnt lgkmcnt(0)
	v_add_f32_e32 v52, v68, v69
	v_mov_b32_e32 v53, v52
	s_nop 1
	v_permlane32_swap_b32_e32 v52, v53
	v_lshlrev_b64 v[66:67], 11, v[64:65]
	v_lshl_add_u64 v[66:67], s[10:11], 0, v[66:67]
	v_lshl_add_u64 v[66:67], v[144:145], 1, v[66:67]
	v_cvt_pk_bf16_f32 v63, v58, v59
	v_cvt_pk_bf16_f32 v57, v54, v55
	v_cvt_pk_bf16_f32 v58, v48, v49
	v_cvt_pk_bf16_f32 v59, v50, v51
	global_store_dwordx4 v[66:67], v[60:63], off
	global_store_dwordx4 v[66:67], v[56:59], off offset:256
	s_and_saveexec_b64 s[16:17], s[0:1]
	s_cbranch_execz .LBB0_1284
	v_lshl_add_u64 v[48:49], v[64:65], 2, s[12:13]
	s_waitcnt lgkmcnt(0)
	v_add_f32_e32 v50, v52, v53
	global_atomic_add_f32 v[48:49], v50, off
.LBB0_1284:
	s_or_b64 exec, exec, s[16:17]
	v_mul_f32_e32 v52, v45, v45
	s_waitcnt lgkmcnt(0)
	v_mul_f32_e32 v53, v47, v47
	v_fmac_f32_e32 v52, v44, v44
	v_fmac_f32_e32 v53, v46, v46
	v_cvt_pk_bf16_f32 v44, v44, v45
	v_cvt_pk_bf16_f32 v45, v46, v47
	v_mul_f32_e32 v46, v37, v37
	v_mul_f32_e32 v47, v39, v39
	v_fmac_f32_e32 v46, v36, v36
	v_fmac_f32_e32 v47, v38, v38
	v_add_f32_e32 v52, v52, v53
	v_mul_f32_e32 v53, v41, v41
	v_add_f32_e32 v46, v46, v47
	v_mul_f32_e32 v47, v33, v33
	v_fmac_f32_e32 v53, v40, v40
	v_fmac_f32_e32 v47, v32, v32
	v_add_f32_e32 v52, v52, v53
	v_mul_f32_e32 v53, v43, v43
	v_add_f32_e32 v46, v46, v47
	v_mul_f32_e32 v47, v35, v35
	v_fmac_f32_e32 v53, v42, v42
	v_fmac_f32_e32 v47, v34, v34
	v_add_f32_e32 v52, v53, v52
	v_add_f32_e32 v46, v47, v46
	v_add_f32_e32 v52, v52, v46
	v_mov_b32_e32 v53, v52
	s_nop 1
	v_permlane16_swap_b32_e32 v52, v53
	v_cvt_pk_bf16_f32 v46, v40, v41
	v_cvt_pk_bf16_f32 v40, v36, v37
	v_add_u32_e32 v48, 0x90, v146
	v_ashrrev_i32_e32 v49, 31, v48
	s_waitcnt lgkmcnt(0)
	v_add_f32_e32 v36, v52, v53
	v_mov_b32_e32 v37, v36
	s_nop 1
	v_permlane32_swap_b32_e32 v36, v37
	v_lshlrev_b64 v[50:51], 11, v[48:49]
	v_lshl_add_u64 v[50:51], s[10:11], 0, v[50:51]
	v_lshl_add_u64 v[50:51], v[144:145], 1, v[50:51]
	v_cvt_pk_bf16_f32 v47, v42, v43
	v_cvt_pk_bf16_f32 v41, v38, v39
	v_cvt_pk_bf16_f32 v42, v32, v33
	v_cvt_pk_bf16_f32 v43, v34, v35
	global_store_dwordx4 v[50:51], v[44:47], off
	global_store_dwordx4 v[50:51], v[40:43], off offset:256
	s_and_saveexec_b64 s[16:17], s[0:1]
	s_cbranch_execz .LBB0_1286
	v_lshl_add_u64 v[32:33], v[48:49], 2, s[12:13]
	s_waitcnt lgkmcnt(0)
	v_add_f32_e32 v34, v36, v37
	global_atomic_add_f32 v[32:33], v34, off
.LBB0_1286:
	s_or_b64 exec, exec, s[16:17]
	v_mul_f32_e32 v36, v29, v29
	s_waitcnt lgkmcnt(0)
	v_mul_f32_e32 v37, v31, v31
	v_fmac_f32_e32 v36, v28, v28
	v_fmac_f32_e32 v37, v30, v30
	v_cvt_pk_bf16_f32 v28, v28, v29
	v_cvt_pk_bf16_f32 v29, v30, v31
	v_mul_f32_e32 v30, v21, v21
	v_mul_f32_e32 v31, v23, v23
	v_fmac_f32_e32 v30, v20, v20
	v_fmac_f32_e32 v31, v22, v22
	v_add_f32_e32 v36, v36, v37
	v_mul_f32_e32 v37, v25, v25
	v_add_f32_e32 v30, v30, v31
	v_mul_f32_e32 v31, v17, v17
	v_fmac_f32_e32 v37, v24, v24
	v_fmac_f32_e32 v31, v16, v16
	v_add_f32_e32 v36, v36, v37
	v_mul_f32_e32 v37, v27, v27
	v_add_f32_e32 v30, v30, v31
	v_mul_f32_e32 v31, v19, v19
	v_fmac_f32_e32 v37, v26, v26
	v_fmac_f32_e32 v31, v18, v18
	v_add_f32_e32 v36, v37, v36
	v_add_f32_e32 v30, v31, v30
	v_add_f32_e32 v36, v36, v30
	v_mov_b32_e32 v37, v36
	s_nop 1
	v_permlane16_swap_b32_e32 v36, v37
	v_cvt_pk_bf16_f32 v30, v24, v25
	v_cvt_pk_bf16_f32 v24, v20, v21
	v_add_u32_e32 v32, 0xa0, v146
	v_ashrrev_i32_e32 v33, 31, v32
	s_waitcnt lgkmcnt(0)
	v_add_f32_e32 v20, v36, v37
	v_mov_b32_e32 v21, v20
	s_nop 1
	v_permlane32_swap_b32_e32 v20, v21
	v_lshlrev_b64 v[34:35], 11, v[32:33]
	v_lshl_add_u64 v[34:35], s[10:11], 0, v[34:35]
	v_lshl_add_u64 v[34:35], v[144:145], 1, v[34:35]
	v_cvt_pk_bf16_f32 v31, v26, v27
	v_cvt_pk_bf16_f32 v25, v22, v23
	v_cvt_pk_bf16_f32 v26, v16, v17
	v_cvt_pk_bf16_f32 v27, v18, v19
	global_store_dwordx4 v[34:35], v[28:31], off
	global_store_dwordx4 v[34:35], v[24:27], off offset:256
	s_and_saveexec_b64 s[16:17], s[0:1]
	s_cbranch_execz .LBB0_1288
	v_lshl_add_u64 v[16:17], v[32:33], 2, s[12:13]
	s_waitcnt lgkmcnt(0)
	v_add_f32_e32 v18, v20, v21
	global_atomic_add_f32 v[16:17], v18, off
.LBB0_1288:
	s_or_b64 exec, exec, s[16:17]
	v_mul_f32_e32 v20, v13, v13
	s_waitcnt lgkmcnt(0)
	v_mul_f32_e32 v21, v15, v15
	v_fmac_f32_e32 v20, v12, v12
	v_fmac_f32_e32 v21, v14, v14
	v_cvt_pk_bf16_f32 v12, v12, v13
	v_cvt_pk_bf16_f32 v13, v14, v15
	v_mul_f32_e32 v14, v5, v5
	v_mul_f32_e32 v15, v7, v7
	v_fmac_f32_e32 v14, v4, v4
	v_fmac_f32_e32 v15, v6, v6
	v_add_f32_e32 v20, v20, v21
	v_mul_f32_e32 v21, v9, v9
	v_add_f32_e32 v14, v14, v15
	v_mul_f32_e32 v15, v1, v1
	v_fmac_f32_e32 v21, v8, v8
	v_fmac_f32_e32 v15, v0, v0
	v_add_f32_e32 v20, v20, v21
	v_mul_f32_e32 v21, v11, v11
	v_add_f32_e32 v14, v14, v15
	v_mul_f32_e32 v15, v3, v3
	v_fmac_f32_e32 v21, v10, v10
	v_fmac_f32_e32 v15, v2, v2
	v_add_f32_e32 v20, v21, v20
	v_add_f32_e32 v14, v15, v14
	v_add_f32_e32 v20, v20, v14
	v_mov_b32_e32 v21, v20
	s_nop 1
	v_permlane16_swap_b32_e32 v20, v21
	v_cvt_pk_bf16_f32 v14, v8, v9
	v_cvt_pk_bf16_f32 v8, v4, v5
	v_add_u32_e32 v16, 0xb0, v146
	v_ashrrev_i32_e32 v17, 31, v16
	s_waitcnt lgkmcnt(0)
	v_add_f32_e32 v4, v20, v21
	v_mov_b32_e32 v5, v4
	s_nop 1
	v_permlane32_swap_b32_e32 v4, v5
	v_lshlrev_b64 v[18:19], 11, v[16:17]
	v_lshl_add_u64 v[18:19], s[10:11], 0, v[18:19]
	v_lshl_add_u64 v[18:19], v[144:145], 1, v[18:19]
	v_cvt_pk_bf16_f32 v15, v10, v11
	v_cvt_pk_bf16_f32 v9, v6, v7
	v_cvt_pk_bf16_f32 v10, v0, v1
	v_cvt_pk_bf16_f32 v11, v2, v3
	global_store_dwordx4 v[18:19], v[12:15], off
	global_store_dwordx4 v[18:19], v[8:11], off offset:256
	s_and_saveexec_b64 s[16:17], s[0:1]
	s_cbranch_execz .LBB0_1261
	v_lshl_add_u64 v[0:1], v[16:17], 2, s[12:13]
	s_waitcnt lgkmcnt(0)
	v_add_f32_e32 v2, v4, v5
	global_atomic_add_f32 v[0:1], v2, off
	s_branch .LBB0_1261
